# NSA selected/window: V^T fragments loaded as one dwordx4 per 16 rows (8 consecutive keys per lane; K rows and masks/ALiBi constants permuted to match) -- halves vector-memory line accesses
# speedup vs baseline: 1.0619x; 1.0237x over previous
.LBB0_188:
	v_lshl_add_u64 v[0:1], s[86:87], 0, v[104:105]
	s_mov_b32 s1, 0x15200000
	v_add_co_u32_e32 v0, vcc, s1, v0
	v_cvt_f32_u32_e32 v107, s82
	s_nop 0
	v_addc_co_u32_e32 v1, vcc, 0, v1, vcc
	global_load_dwordx4 v[4:7], v[0:1], off
	s_nop 0
	global_load_dwordx4 v[0:3], v[0:1], off offset:64
	v_cmp_lt_f32_e32 vcc, s72, v107
	s_nop 1
	v_cndmask_b32_e32 v108, 0, v220, vcc
	v_sub_f32_e32 v107, v108, v107
	v_exp_f32_e32 v107, v107
	s_and_b64 vcc, vcc, exec
	s_cselect_b32 s1, 0xffffffc0, 0
	v_ldexp_f32 v152, v107, s1
	global_load_dwordx4 v[108:111], v[16:17], off
	global_load_dwordx4 v[196:199], v[16:17], off offset:64
	global_load_dwordx4 v[112:115], v[16:17], off offset:2048
	global_load_dwordx4 v[200:203], v[16:17], off offset:2112
	global_load_dwordx4 v[116:119], v[26:27], off
	global_load_dwordx4 v[204:207], v[28:29], off
	global_load_dwordx4 v[120:123], v[36:37], off
	global_load_dwordx4 v[228:231], v[38:39], off
	global_load_dwordx4 v[124:127], v[44:45], off
	global_load_dwordx4 v[232:235], v[46:47], off
	global_load_dwordx4 v[128:131], v[52:53], off
	global_load_dwordx4 v[236:239], v[54:55], off
	global_load_dwordx4 v[132:135], v[60:61], off
	global_load_dwordx4 v[136:139], v[68:69], off
	global_load_dwordx4 v[140:143], v[62:63], off
	global_load_dwordx4 v[148:151], v[70:71], off
	s_waitcnt vmcnt(14) lgkmcnt(0)
	v_mfma_f32_16x16x32_bf16 v[108:111], v[108:111], v[4:7], 0
	v_mfma_f32_16x16x32_bf16 v[108:111], v[196:199], v[0:3], v[108:111]
	s_waitcnt vmcnt(12)
	v_mfma_f32_16x16x32_bf16 v[112:115], v[112:115], v[4:7], 0
	v_mfma_f32_16x16x32_bf16 v[112:115], v[200:203], v[0:3], v[112:115]
	s_waitcnt vmcnt(10)
	v_mfma_f32_16x16x32_bf16 v[116:119], v[116:119], v[4:7], 0
	v_mfma_f32_16x16x32_bf16 v[116:119], v[204:207], v[0:3], v[116:119]
	s_waitcnt vmcnt(8)
	v_mfma_f32_16x16x32_bf16 v[120:123], v[120:123], v[4:7], 0
	v_mfma_f32_16x16x32_bf16 v[120:123], v[228:231], v[0:3], v[120:123]
	s_waitcnt vmcnt(6)
	v_mfma_f32_16x16x32_bf16 v[124:127], v[124:127], v[4:7], 0
	v_mfma_f32_16x16x32_bf16 v[124:127], v[232:235], v[0:3], v[124:127]
	s_waitcnt vmcnt(4)
	v_mfma_f32_16x16x32_bf16 v[128:131], v[128:131], v[4:7], 0
	v_mfma_f32_16x16x32_bf16 v[128:131], v[236:239], v[0:3], v[128:131]
	v_pk_mul_f32 v[154:155], v[22:23], v[152:153] op_sel_hi:[1,0]
	v_pk_mul_f32 v[156:157], v[24:25], v[152:153] op_sel_hi:[1,0]
	v_pk_mul_f32 v[180:181], v[40:41], v[152:153] op_sel_hi:[1,0]
	v_pk_mul_f32 v[182:183], v[42:43], v[152:153] op_sel_hi:[1,0]
	v_pk_mul_f32 v[188:189], v[18:19], v[152:153] op_sel_hi:[1,0]
	v_pk_mul_f32 v[158:159], v[72:73], v[152:153] op_sel_hi:[1,0]
	v_pk_mul_f32 v[166:167], v[74:75], v[152:153] op_sel_hi:[1,0]
	v_pk_mul_f32 v[168:169], v[64:65], v[152:153] op_sel_hi:[1,0]
	v_pk_mul_f32 v[170:171], v[66:67], v[152:153] op_sel_hi:[1,0]
	v_pk_mul_f32 v[172:173], v[56:57], v[152:153] op_sel_hi:[1,0]
	v_pk_mul_f32 v[174:175], v[58:59], v[152:153] op_sel_hi:[1,0]
	v_pk_mul_f32 v[176:177], v[48:49], v[152:153] op_sel_hi:[1,0]
	v_pk_mul_f32 v[178:179], v[50:51], v[152:153] op_sel_hi:[1,0]
	v_pk_mul_f32 v[184:185], v[30:31], v[152:153] op_sel_hi:[1,0]
	v_pk_mul_f32 v[186:187], v[34:35], v[152:153] op_sel_hi:[1,0]
	v_pk_mul_f32 v[152:153], v[20:21], v[152:153] op_sel_hi:[1,0]
	v_pk_fma_f32 v[112:113], v[112:113], s[90:91], v[154:155] op_sel_hi:[1,0,1] neg_lo:[0,0,1] neg_hi:[0,0,1]
	v_pk_fma_f32 v[114:115], v[114:115], s[90:91], v[156:157] op_sel_hi:[1,0,1] neg_lo:[0,0,1] neg_hi:[0,0,1]
	v_pk_fma_f32 v[120:121], v[120:121], s[90:91], v[180:181] op_sel_hi:[1,0,1] neg_lo:[0,0,1] neg_hi:[0,0,1]
	v_pk_fma_f32 v[122:123], v[122:123], s[90:91], v[182:183] op_sel_hi:[1,0,1] neg_lo:[0,0,1] neg_hi:[0,0,1]
	v_pk_fma_f32 v[108:109], v[108:109], s[90:91], v[188:189] op_sel_hi:[1,0,1] neg_lo:[0,0,1] neg_hi:[0,0,1]
	v_pk_fma_f32 v[110:111], v[110:111], s[90:91], v[152:153] op_sel_hi:[1,0,1] neg_lo:[0,0,1] neg_hi:[0,0,1]
	v_cndmask_b32_e64 v107, v221, v113, s[14:15]
	v_cndmask_b32_e64 v113, v221, v115, s[16:17]
	v_cndmask_b32_e64 v115, v221, v121, s[34:35]
	v_cndmask_b32_e64 v121, v221, v123, s[36:37]
	v_cndmask_b32_e64 v123, v221, v109, s[6:7]
	v_cndmask_b32_e64 v152, v221, v108, s[4:5]
	v_cndmask_b32_e64 v153, v221, v111, s[8:9]
	v_cndmask_b32_e64 v154, v221, v110, s[10:11]
	v_max3_f32 v108, v152, s73, v123
	v_cndmask_b32_e64 v112, v221, v112, s[12:13]
	v_max3_f32 v108, v108, v154, v153
	v_pk_fma_f32 v[116:117], v[116:117], s[90:91], v[184:185] op_sel_hi:[1,0,1] neg_lo:[0,0,1] neg_hi:[0,0,1]
	v_cndmask_b32_e64 v114, v221, v114, s[20:21]
	v_max3_f32 v155, v108, v112, v107
	v_pk_fma_f32 v[118:119], v[118:119], s[90:91], v[186:187] op_sel_hi:[1,0,1] neg_lo:[0,0,1] neg_hi:[0,0,1]
	v_cndmask_b32_e64 v117, v221, v117, s[24:25]
	v_cndmask_b32_e64 v116, v221, v116, s[22:23]
	v_cndmask_b32_e64 v119, v221, v119, s[26:27]
	v_cndmask_b32_e64 v118, v221, v118, s[28:29]
	v_cndmask_b32_e64 v120, v221, v120, s[30:31]
	v_pk_fma_f32 v[124:125], v[124:125], s[90:91], v[176:177] op_sel_hi:[1,0,1] neg_lo:[0,0,1] neg_hi:[0,0,1]
	v_cndmask_b32_e64 v122, v221, v122, s[38:39]
	v_pk_fma_f32 v[126:127], v[126:127], s[90:91], v[178:179] op_sel_hi:[1,0,1] neg_lo:[0,0,1] neg_hi:[0,0,1]
	v_cndmask_b32_e64 v125, v221, v125, s[44:45]
	v_cndmask_b32_e64 v124, v221, v124, s[42:43]
	v_pk_fma_f32 v[128:129], v[128:129], s[90:91], v[172:173] op_sel_hi:[1,0,1] neg_lo:[0,0,1] neg_hi:[0,0,1]
	v_cndmask_b32_e64 v127, v221, v127, s[40:41]
	v_cndmask_b32_e64 v126, v221, v126, s[46:47]
	v_pk_fma_f32 v[130:131], v[130:131], s[90:91], v[174:175] op_sel_hi:[1,0,1] neg_lo:[0,0,1] neg_hi:[0,0,1]
	v_cndmask_b32_e64 v129, v221, v129, s[52:53]
	v_cndmask_b32_e64 v128, v221, v128, s[50:51]
	v_cndmask_b32_e64 v131, v221, v131, s[48:49]
	v_cndmask_b32_e64 v130, v221, v130, s[54:55]
	v_cmp_lt_f32_e32 vcc, s92, v123
	s_waitcnt vmcnt(0) lgkmcnt(0)
	v_mfma_f32_16x16x32_bf16 v[108:111], v[132:135], v[4:7], 0
	v_max3_f32 v132, v155, v114, v113
	v_max3_f32 v132, v132, v116, v117
	v_max3_f32 v132, v132, v118, v119
	v_mfma_f32_16x16x32_bf16 v[4:7], v[136:139], v[4:7], 0
	v_max3_f32 v132, v132, v120, v115
	v_max3_f32 v132, v132, v122, v121
	v_max3_f32 v132, v132, v124, v125
	v_mfma_f32_16x16x32_bf16 v[108:111], v[140:143], v[0:3], v[108:111]
	v_max3_f32 v132, v132, v126, v127
	v_max3_f32 v132, v132, v128, v129
	v_max3_f32 v132, v132, v130, v131
	v_mfma_f32_16x16x32_bf16 v[0:3], v[148:151], v[0:3], v[4:7]
	s_nop 3
	v_fma_f32 v4, v108, s90, -v168
	v_fma_f32 v5, v109, s90, -v169
	s_nop 1
	v_pk_fma_f32 v[0:1], v[0:1], s[90:91], v[158:159] op_sel_hi:[1,0,1] neg_lo:[0,0,1] neg_hi:[0,0,1]
	v_pk_fma_f32 v[6:7], v[110:111], s[90:91], v[170:171] op_sel_hi:[1,0,1] neg_lo:[0,0,1] neg_hi:[0,0,1]
	v_cndmask_b32_e64 v137, v221, v5, s[60:61]
	v_cndmask_b32_e64 v138, v221, v4, s[58:59]
	v_cndmask_b32_e64 v134, v221, v0, s[66:67]
	v_cndmask_b32_e64 v139, v221, v7, s[56:57]
	v_cndmask_b32_e64 v140, v221, v6, s[62:63]
	v_max3_f32 v0, v132, v138, v137
	v_pk_fma_f32 v[2:3], v[2:3], s[90:91], v[166:167] op_sel_hi:[1,0,1] neg_lo:[0,0,1] neg_hi:[0,0,1]
	v_cndmask_b32_e64 v133, v221, v1, s[68:69]
	v_max3_f32 v0, v0, v140, v139
	v_cndmask_b32_e64 v135, v221, v3, s[64:65]
	v_cndmask_b32_e64 v136, v221, v2, s[70:71]
	v_max3_f32 v0, v0, v134, v133
	v_max3_f32 v0, v0, v136, v135
	ds_bpermute_b32 v1, v193, v0
	s_waitcnt lgkmcnt(0)
	v_max_f32_e32 v1, v1, v1
	v_max_f32_e32 v0, v0, v1
	ds_bpermute_b32 v1, v194, v0
	s_waitcnt lgkmcnt(0)
	v_max_f32_e32 v1, v1, v1
	v_max_f32_e32 v132, v0, v1
	v_sub_f32_e32 v1, v123, v132
	v_sub_f32_e32 v0, v152, v132
	v_mul_f32_e32 v1, 0x3fb8aa3b, v1
	v_sub_f32_e32 v3, v153, v132
	v_mul_f32_e32 v0, 0x3fb8aa3b, v0
	v_exp_f32_e32 v1, v1
	v_sub_f32_e32 v2, v154, v132
	v_mul_f32_e32 v3, 0x3fb8aa3b, v3
	v_exp_f32_e32 v0, v0
	v_sub_f32_e32 v5, v107, v132
	v_mul_f32_e32 v2, 0x3fb8aa3b, v2
	v_exp_f32_e32 v3, v3
	v_sub_f32_e32 v4, v112, v132
	v_mul_f32_e32 v5, 0x3fb8aa3b, v5
	v_exp_f32_e32 v2, v2
	v_mul_f32_e32 v4, 0x3fb8aa3b, v4
	v_exp_f32_e32 v5, v5
	v_cndmask_b32_e32 v1, 0, v1, vcc
	v_cmp_lt_f32_e32 vcc, s92, v152
	v_exp_f32_e32 v4, v4
	v_sub_f32_e32 v7, v113, v132
	v_cndmask_b32_e32 v0, 0, v0, vcc
	v_cmp_lt_f32_e32 vcc, s92, v153
	v_add_f32_e32 v6, 0, v0
	v_add_f32_e32 v6, v1, v6
	v_cndmask_b32_e32 v3, 0, v3, vcc
	v_cmp_lt_f32_e32 vcc, s92, v154
	v_mul_f32_e32 v7, 0x3fb8aa3b, v7
	v_exp_f32_e32 v7, v7
	v_cndmask_b32_e32 v2, 0, v2, vcc
	v_cmp_lt_f32_e32 vcc, s92, v107
	v_add_f32_e32 v6, v2, v6
	v_add_f32_e32 v6, v3, v6
	v_cndmask_b32_e32 v5, 0, v5, vcc
	v_cmp_lt_f32_e32 vcc, s92, v112
	v_sub_f32_e32 v109, v117, v132
	v_sub_f32_e32 v108, v116, v132
	v_cndmask_b32_e32 v4, 0, v4, vcc
	v_add_f32_e32 v6, v4, v6
	v_add_f32_e32 v107, v5, v6
	v_sub_f32_e32 v6, v114, v132
	v_mul_f32_e32 v6, 0x3fb8aa3b, v6
	v_exp_f32_e32 v6, v6
	v_mul_f32_e32 v109, 0x3fb8aa3b, v109
	v_exp_f32_e32 v109, v109
	v_mul_f32_e32 v108, 0x3fb8aa3b, v108
	v_sub_f32_e32 v111, v119, v132
	v_cmp_lt_f32_e32 vcc, s92, v113
	v_exp_f32_e32 v108, v108
	v_sub_f32_e32 v110, v118, v132
	v_mul_f32_e32 v111, 0x3fb8aa3b, v111
	v_cndmask_b32_e32 v7, 0, v7, vcc
	v_cmp_lt_f32_e32 vcc, s92, v114
	v_exp_f32_e32 v111, v111
	v_mul_f32_e32 v110, 0x3fb8aa3b, v110
	v_cndmask_b32_e32 v6, 0, v6, vcc
	v_cmp_lt_f32_e32 vcc, s92, v117
	v_exp_f32_e32 v110, v110
	v_sub_f32_e32 v113, v115, v132
	v_cndmask_b32_e32 v109, 0, v109, vcc
	v_cmp_lt_f32_e32 vcc, s92, v116
	v_sub_f32_e32 v112, v120, v132
	v_mul_f32_e32 v113, 0x3fb8aa3b, v113
	v_cndmask_b32_e32 v108, 0, v108, vcc
	v_cmp_lt_f32_e32 vcc, s92, v119
	v_add_f32_e32 v107, v6, v107
	v_exp_f32_e32 v113, v113
	v_cndmask_b32_e32 v111, 0, v111, vcc
	v_cmp_lt_f32_e32 vcc, s92, v118
	v_mul_f32_e32 v112, 0x3fb8aa3b, v112
	v_add_f32_e32 v107, v7, v107
	v_cndmask_b32_e32 v110, 0, v110, vcc
	v_cmp_lt_f32_e32 vcc, s92, v115
	v_sub_f32_e32 v115, v121, v132
	v_exp_f32_e32 v112, v112
	v_sub_f32_e32 v114, v122, v132
	v_mul_f32_e32 v115, 0x3fb8aa3b, v115
	v_add_f32_e32 v107, v108, v107
	v_exp_f32_e32 v115, v115
	v_mul_f32_e32 v114, 0x3fb8aa3b, v114
	v_sub_f32_e32 v117, v125, v132
	v_add_f32_e32 v107, v109, v107
	v_exp_f32_e32 v114, v114
	v_sub_f32_e32 v116, v124, v132
	v_mul_f32_e32 v117, 0x3fb8aa3b, v117
	v_add_f32_e32 v107, v110, v107
	v_cndmask_b32_e32 v113, 0, v113, vcc
	v_cmp_lt_f32_e32 vcc, s92, v120
	v_exp_f32_e32 v117, v117
	v_mul_f32_e32 v116, 0x3fb8aa3b, v116
	v_sub_f32_e32 v119, v127, v132
	v_add_f32_e32 v107, v111, v107
	v_cndmask_b32_e32 v112, 0, v112, vcc
	v_cmp_lt_f32_e32 vcc, s92, v121
	v_exp_f32_e32 v116, v116
	v_sub_f32_e32 v118, v126, v132
	v_mul_f32_e32 v119, 0x3fb8aa3b, v119
	v_add_f32_e32 v107, v112, v107
	v_cndmask_b32_e32 v115, 0, v115, vcc
	v_cmp_lt_f32_e32 vcc, s92, v122
	v_exp_f32_e32 v119, v119
	v_mul_f32_e32 v118, 0x3fb8aa3b, v118
	v_sub_f32_e32 v121, v129, v132
	v_add_f32_e32 v107, v113, v107
	v_cndmask_b32_e32 v114, 0, v114, vcc
	v_cmp_lt_f32_e32 vcc, s92, v125
	v_exp_f32_e32 v118, v118
	v_sub_f32_e32 v120, v128, v132
	v_mul_f32_e32 v121, 0x3fb8aa3b, v121
	v_add_f32_e32 v107, v114, v107
	v_cndmask_b32_e32 v117, 0, v117, vcc
	v_cmp_lt_f32_e32 vcc, s92, v124
	v_exp_f32_e32 v121, v121
	v_mul_f32_e32 v120, 0x3fb8aa3b, v120
	v_sub_f32_e32 v123, v131, v132
	v_add_f32_e32 v107, v115, v107
	v_cndmask_b32_e32 v116, 0, v116, vcc
	v_cmp_lt_f32_e32 vcc, s92, v127
	v_exp_f32_e32 v120, v120
	v_sub_f32_e32 v122, v130, v132
	v_mul_f32_e32 v123, 0x3fb8aa3b, v123
	v_add_f32_e32 v107, v116, v107
	v_cndmask_b32_e32 v119, 0, v119, vcc
	v_cmp_lt_f32_e32 vcc, s92, v126
	v_exp_f32_e32 v123, v123
	v_mul_f32_e32 v122, 0x3fb8aa3b, v122
	v_sub_f32_e32 v125, v137, v132
	v_add_f32_e32 v107, v117, v107
	v_cndmask_b32_e32 v118, 0, v118, vcc
	v_cmp_lt_f32_e32 vcc, s92, v129
	v_exp_f32_e32 v122, v122
	v_sub_f32_e32 v124, v138, v132
	v_mul_f32_e32 v125, 0x3fb8aa3b, v125
	v_add_f32_e32 v107, v118, v107
	v_cndmask_b32_e32 v121, 0, v121, vcc
	v_cmp_lt_f32_e32 vcc, s92, v128
	v_exp_f32_e32 v125, v125
	v_mul_f32_e32 v124, 0x3fb8aa3b, v124
	v_sub_f32_e32 v127, v139, v132
	v_add_f32_e32 v107, v119, v107
	v_cndmask_b32_e32 v120, 0, v120, vcc
	v_cmp_lt_f32_e32 vcc, s92, v131
	v_exp_f32_e32 v124, v124
	v_sub_f32_e32 v126, v140, v132
	v_mul_f32_e32 v127, 0x3fb8aa3b, v127
	v_add_f32_e32 v107, v120, v107
	v_cndmask_b32_e32 v123, 0, v123, vcc
	v_cmp_lt_f32_e32 vcc, s92, v130
	v_exp_f32_e32 v127, v127
	v_mul_f32_e32 v126, 0x3fb8aa3b, v126
	v_sub_f32_e32 v129, v133, v132
	v_add_f32_e32 v107, v121, v107
	v_cndmask_b32_e32 v122, 0, v122, vcc
	v_cmp_lt_f32_e32 vcc, s92, v137
	v_exp_f32_e32 v126, v126
	v_sub_f32_e32 v128, v134, v132
	v_mul_f32_e32 v129, 0x3fb8aa3b, v129
	v_add_f32_e32 v107, v122, v107
	v_cndmask_b32_e32 v125, 0, v125, vcc
	v_cmp_lt_f32_e32 vcc, s92, v138
	v_exp_f32_e32 v129, v129
	v_mul_f32_e32 v128, 0x3fb8aa3b, v128
	v_sub_f32_e32 v131, v135, v132
	v_add_f32_e32 v107, v123, v107
	v_cndmask_b32_e32 v124, 0, v124, vcc
	v_cmp_lt_f32_e32 vcc, s92, v139
	v_exp_f32_e32 v128, v128
	v_sub_f32_e32 v130, v136, v132
	v_mul_f32_e32 v131, 0x3fb8aa3b, v131
	v_add_f32_e32 v107, v124, v107
	v_cndmask_b32_e32 v127, 0, v127, vcc
	v_cmp_lt_f32_e32 vcc, s92, v140
	v_exp_f32_e32 v131, v131
	v_mul_f32_e32 v130, 0x3fb8aa3b, v130
	v_add_f32_e32 v107, v125, v107
	v_cndmask_b32_e32 v126, 0, v126, vcc
	v_cmp_lt_f32_e32 vcc, s92, v133
	v_exp_f32_e32 v130, v130
	v_add_f32_e32 v107, v126, v107
	v_cndmask_b32_e32 v129, 0, v129, vcc
	v_cmp_lt_f32_e32 vcc, s92, v134
	v_add_f32_e32 v107, v127, v107
	s_nop 0
	v_cndmask_b32_e32 v128, 0, v128, vcc
	v_cmp_lt_f32_e32 vcc, s92, v135
	v_add_f32_e32 v107, v128, v107
	v_add_f32_e32 v107, v129, v107
	v_cndmask_b32_e32 v131, 0, v131, vcc
	v_cmp_lt_f32_e32 vcc, s92, v136
	s_nop 1
	v_cndmask_b32_e32 v130, 0, v130, vcc
	v_add_f32_e32 v107, v130, v107
	v_add_f32_e32 v107, v131, v107
	ds_bpermute_b32 v132, v193, v107
	s_waitcnt lgkmcnt(0)
	v_add_f32_e32 v107, v107, v132
	ds_bpermute_b32 v132, v194, v107
	s_waitcnt lgkmcnt(0)
	v_add_f32_e32 v107, v107, v132
	v_div_scale_f32 v132, vcc, v107, v107, 1.0
	v_rcp_f32_e32 v133, v132
	s_nop 0
	v_fma_f32 v134, -v132, v133, 1.0
	v_fmac_f32_e32 v133, v134, v133
	v_div_scale_f32 v134, vcc, 1.0, v107, 1.0
	v_mul_f32_e32 v135, v134, v133
	v_fma_f32 v136, -v132, v135, v134
	v_fmac_f32_e32 v135, v136, v133
	v_fma_f32 v132, -v132, v135, v134
	v_div_fmas_f32 v132, v132, v133, v135
	v_div_fixup_f32 v132, v132, v107, 1.0
	v_cmp_lt_f32_e32 vcc, 0, v107
	s_nop 1
	v_cndmask_b32_e32 v132, 0, v132, vcc
	v_pk_mul_f32 v[134:135], v[2:3], v[132:133] op_sel_hi:[1,0]
	v_pk_mul_f32 v[136:137], v[6:7], v[132:133] op_sel_hi:[1,0]
	ds_bpermute_b32 v2, v33, v135
	ds_bpermute_b32 v107, v33, v137
	v_pk_mul_f32 v[138:139], v[0:1], v[132:133] op_sel_hi:[1,0]
	v_pk_mul_f32 v[140:141], v[4:5], v[132:133] op_sel_hi:[1,0]
	v_mov_b32_e32 v4, v139
	s_waitcnt lgkmcnt(1)
	v_cndmask_b32_e64 v0, 0, v2, s[18:19]
	s_waitcnt lgkmcnt(0)
	v_cndmask_b32_e64 v1, v2, v107, s[18:19]
	v_mov_b32_e32 v2, v138
	v_mov_b32_e32 v3, v140
	v_mov_b32_e32 v5, v141
	v_pk_add_f32 v[2:3], v[2:3], v[4:5]
	v_mov_b32_e32 v4, v134
	v_mov_b32_e32 v5, v136
	v_mov_b32_e32 v6, v135
	v_mov_b32_e32 v7, v137
	v_pk_add_f32 v[4:5], v[4:5], v[6:7]
	v_pk_mul_f32 v[148:149], v[110:111], v[132:133] op_sel_hi:[1,0]
	v_pk_mul_f32 v[152:153], v[114:115], v[132:133] op_sel_hi:[1,0]
	v_pk_add_f32 v[2:3], v[2:3], v[4:5]
	ds_bpermute_b32 v6, v33, v149
	ds_bpermute_b32 v7, v33, v153
	v_pk_add_f32 v[0:1], v[0:1], v[2:3]
	v_pk_mul_f32 v[142:143], v[108:109], v[132:133] op_sel_hi:[1,0]
	v_pk_mul_f32 v[150:151], v[112:113], v[132:133] op_sel_hi:[1,0]
	v_pk_add_f32 v[14:15], v[14:15], v[0:1]
	v_mov_b32_e32 v0, v142
	v_mov_b32_e32 v1, v150
	v_mov_b32_e32 v2, v143
	v_mov_b32_e32 v3, v151
	v_pk_add_f32 v[0:1], v[0:1], v[2:3]
	v_mov_b32_e32 v2, v148
	v_mov_b32_e32 v3, v152
	v_mov_b32_e32 v4, v149
	v_mov_b32_e32 v5, v153
	v_pk_add_f32 v[2:3], v[2:3], v[4:5]
	v_pk_mul_f32 v[156:157], v[118:119], v[132:133] op_sel_hi:[1,0]
	v_pk_mul_f32 v[166:167], v[122:123], v[132:133] op_sel_hi:[1,0]
	v_pk_add_f32 v[0:1], v[0:1], v[2:3]
	s_waitcnt lgkmcnt(0)
	v_cndmask_b32_e64 v3, v6, v7, s[18:19]
	v_cndmask_b32_e64 v2, v107, v6, s[18:19]
	ds_bpermute_b32 v6, v33, v157
	ds_bpermute_b32 v107, v33, v167
	v_pk_add_f32 v[0:1], v[0:1], v[2:3]
	v_pk_mul_f32 v[154:155], v[116:117], v[132:133] op_sel_hi:[1,0]
	v_pk_mul_f32 v[158:159], v[120:121], v[132:133] op_sel_hi:[1,0]
	v_pk_add_f32 v[12:13], v[12:13], v[0:1]
	v_mov_b32_e32 v0, v154
	v_mov_b32_e32 v1, v158
	v_mov_b32_e32 v2, v155
	v_mov_b32_e32 v3, v159
	v_pk_add_f32 v[0:1], v[0:1], v[2:3]
	v_mov_b32_e32 v2, v156
	v_mov_b32_e32 v3, v166
	v_mov_b32_e32 v4, v157
	v_mov_b32_e32 v5, v167
	v_pk_add_f32 v[2:3], v[2:3], v[4:5]
	v_pk_mul_f32 v[4:5], v[128:129], v[132:133] op_sel_hi:[1,0]
	v_pk_add_f32 v[0:1], v[0:1], v[2:3]
	s_waitcnt lgkmcnt(0)
	v_cndmask_b32_e64 v3, v6, v107, s[18:19]
	v_cndmask_b32_e64 v2, v7, v6, s[18:19]
	v_pk_add_f32 v[0:1], v[0:1], v[2:3]
	v_pk_mul_f32 v[2:3], v[126:127], v[132:133] op_sel_hi:[1,0]
	v_pk_mul_f32 v[6:7], v[130:131], v[132:133] op_sel_hi:[1,0]
	ds_bpermute_b32 v114, v33, v3
	ds_bpermute_b32 v115, v33, v7
	v_pk_add_f32 v[10:11], v[10:11], v[0:1]
	v_pk_mul_f32 v[0:1], v[124:125], v[132:133] op_sel_hi:[1,0]
	v_mov_b32_e32 v109, v4
	v_mov_b32_e32 v108, v0
	v_mov_b32_e32 v110, v1
	v_mov_b32_e32 v111, v5
	v_pk_add_f32 v[108:109], v[108:109], v[110:111]
	v_mov_b32_e32 v110, v2
	v_mov_b32_e32 v111, v6
	v_mov_b32_e32 v112, v3
	v_mov_b32_e32 v113, v7
	v_pk_add_f32 v[110:111], v[110:111], v[112:113]
	s_nop 0
	v_pk_add_f32 v[108:109], v[108:109], v[110:111]
	s_waitcnt lgkmcnt(0)
	v_cndmask_b32_e64 v111, v114, v115, s[18:19]
	v_cndmask_b32_e64 v110, v107, v114, s[18:19]
	v_pk_add_f32 v[108:109], v[108:109], v[110:111]
	s_nop 0
	v_pk_add_f32 v[8:9], v[8:9], v[108:109]
	global_load_dwordx2 v[108:109], v[76:77], off
	global_load_dwordx2 v[110:111], v[76:77], off offset:32
	global_load_dwordx2 v[112:113], v[78:79], off
	global_load_dwordx2 v[114:115], v[78:79], off offset:32
	global_load_dwordx2 v[120:121], v[80:81], off
	global_load_dwordx2 v[122:123], v[80:81], off offset:32
	global_load_dwordx2 v[124:125], v[82:83], off
	global_load_dwordx2 v[126:127], v[82:83], off offset:32
	global_load_dwordx2 v[128:129], v[76:77], off offset:64
	global_load_dwordx2 v[130:131], v[76:77], off offset:96
	global_load_dwordx2 v[196:197], v[84:85], off
	global_load_dwordx2 v[198:199], v[84:85], off offset:32
	global_load_dwordx2 v[200:201], v[86:87], off
	global_load_dwordx2 v[202:203], v[86:87], off offset:32
	global_load_dwordx2 v[204:205], v[88:89], off
	global_load_dwordx2 v[206:207], v[88:89], off offset:32
	global_load_dwordx2 v[228:229], v[76:77], off offset:128
	global_load_dwordx2 v[230:231], v[76:77], off offset:160
	global_load_dwordx2 v[232:233], v[90:91], off
	global_load_dwordx2 v[234:235], v[90:91], off offset:32
	global_load_dwordx2 v[236:237], v[92:93], off
	global_load_dwordx2 v[238:239], v[92:93], off offset:32
	global_load_dwordx2 v[240:241], v[94:95], off
	global_load_dwordx2 v[242:243], v[94:95], off offset:32
	global_load_dwordx2 v[244:245], v[76:77], off offset:192
	global_load_dwordx2 v[246:247], v[76:77], off offset:224
	global_load_dwordx2 v[248:249], v[96:97], off
	global_load_dwordx2 v[250:251], v[96:97], off offset:32
	v_cvt_pk_bf16_f32 v116, v138, v139
	v_cvt_pk_bf16_f32 v117, v134, v135
	v_cvt_pk_bf16_f32 v118, v140, v141
	v_cvt_pk_bf16_f32 v119, v136, v137
	s_waitcnt vmcnt(20) lgkmcnt(0)
	s_nop 0
	v_mfma_f32_16x16x32_bf16 v[108:111], v[108:111], v[116:119], 0
	v_mfma_f32_16x16x32_bf16 v[112:115], v[112:115], v[116:119], 0
	v_mfma_f32_16x16x32_bf16 v[120:123], v[120:123], v[116:119], 0
	v_mfma_f32_16x16x32_bf16 v[116:119], v[124:127], v[116:119], 0
	v_cvt_pk_bf16_f32 v124, v142, v143
	v_cvt_pk_bf16_f32 v125, v148, v149
	v_cvt_pk_bf16_f32 v126, v150, v151
	v_cvt_pk_bf16_f32 v127, v152, v153
	s_waitcnt vmcnt(12)
	s_nop 0
	v_mfma_f32_16x16x32_bf16 v[108:111], v[128:131], v[124:127], v[108:111]
	v_mfma_f32_16x16x32_bf16 v[112:115], v[196:199], v[124:127], v[112:115]
	v_mfma_f32_16x16x32_bf16 v[120:123], v[200:203], v[124:127], v[120:123]
	v_mfma_f32_16x16x32_bf16 v[116:119], v[204:207], v[124:127], v[116:119]
	global_load_dwordx2 v[196:197], v[98:99], off
	global_load_dwordx2 v[198:199], v[98:99], off offset:32
	global_load_dwordx2 v[200:201], v[100:101], off
	global_load_dwordx2 v[202:203], v[100:101], off offset:32
	global_load_dword v107, v102, s[86:87]
	v_cvt_pk_bf16_f32 v124, v154, v155
	v_cvt_pk_bf16_f32 v125, v156, v157
	v_cvt_pk_bf16_f32 v126, v158, v159
	v_cvt_pk_bf16_f32 v127, v166, v167
	s_waitcnt vmcnt(9)
	s_nop 0
	v_mfma_f32_16x16x32_bf16 v[108:111], v[228:231], v[124:127], v[108:111]
	v_mfma_f32_16x16x32_bf16 v[112:115], v[232:235], v[124:127], v[112:115]
	v_mfma_f32_16x16x32_bf16 v[120:123], v[236:239], v[124:127], v[120:123]
	v_mfma_f32_16x16x32_bf16 v[116:119], v[240:243], v[124:127], v[116:119]
	v_cvt_pk_bf16_f32 v0, v0, v1
	v_cvt_pk_bf16_f32 v1, v2, v3
	v_cvt_pk_bf16_f32 v2, v4, v5
	v_cvt_pk_bf16_f32 v3, v6, v7
	s_waitcnt vmcnt(5)
	s_nop 0
	v_mfma_f32_16x16x32_bf16 v[4:7], v[244:247], v[0:3], v[108:111]
	s_nop 2
	v_mfma_f32_16x16x32_bf16 v[108:111], v[248:251], v[0:3], v[112:115]
	s_waitcnt vmcnt(1)
	s_nop 1
	v_mfma_f32_16x16x32_bf16 v[112:115], v[196:199], v[0:3], v[120:123]
	v_mfma_f32_16x16x32_bf16 v[0:3], v[200:203], v[0:3], v[116:119]
	s_nop 2
	v_add_u32_e32 v116, s0, v192
	s_waitcnt vmcnt(0) lgkmcnt(0)
	v_mul_f32_e32 v107, 0xbfb8aa3b, v107
	v_exp_f32_e32 v107, v107
	s_nop 0
	v_add_f32_e32 v107, 1.0, v107
	v_rcp_f32_e32 v107, v107
	s_nop 0
	v_mul_f32_e32 v4, v4, v107
	v_mul_f32_e32 v5, v5, v107
	ds_write2st64_b32 v116, v4, v5 offset1:1
	v_mul_f32_e32 v4, v6, v107
	v_mul_f32_e32 v5, v7, v107
	ds_write2st64_b32 v116, v4, v5 offset0:2 offset1:3
	v_mul_f32_e32 v4, v108, v107
	v_mul_f32_e32 v5, v109, v107
	ds_write2st64_b32 v116, v4, v5 offset0:4 offset1:5
	v_mul_f32_e32 v4, v110, v107
	v_mul_f32_e32 v5, v111, v107
	ds_write2st64_b32 v116, v4, v5 offset0:6 offset1:7
	v_mul_f32_e32 v4, v112, v107
	v_mul_f32_e32 v5, v113, v107
	v_mul_f32_e32 v0, v0, v107
	v_mul_f32_e32 v1, v1, v107
	ds_write2st64_b32 v116, v4, v5 offset0:8 offset1:9
	v_mul_f32_e32 v4, v114, v107
	v_mul_f32_e32 v5, v115, v107
	ds_write2st64_b32 v116, v0, v1 offset0:12 offset1:13
	v_mul_f32_e32 v0, v2, v107
	v_mul_f32_e32 v1, v3, v107
	ds_write2st64_b32 v116, v4, v5 offset0:10 offset1:11
	ds_write2st64_b32 v116, v0, v1 offset0:14 offset1:15
	s_addk_i32 s0, 0x1000
	s_add_i32 s82, s82, 1
	v_lshl_add_u64 v[102:103], v[102:103], 0, 12
	s_cmpk_eq_i32 s0, 0x4000
	v_lshl_add_u64 v[104:105], v[104:105], 0, s[96:97]
	s_cbranch_scc0 .LBB0_188
	s_or_b32 s0, s95, s81
	v_or_b32_e32 v0, s0, v190
	v_ashrrev_i32_e32 v1, 31, v0
	v_lshlrev_b64 v[2:3], 7, v[0:1]
	v_lshl_add_u64 v[2:3], s[86:87], 0, v[2:3]
	s_mul_i32 s82, s2, 48
	v_lshl_add_u64 v[2:3], v[2:3], 0, s[82:83]
	s_mov_b64 s[0:1], 0x2f200020
	v_lshl_add_u64 v[148:149], v[2:3], 0, s[0:1]
	s_lshl_b32 s0, s2, 2
	s_or_b32 s1, s0, 1
	v_cvt_f32_ubyte0_e32 v2, s1
	v_cmp_lt_f32_e32 vcc, s72, v2
	s_or_b32 s1, s0, 2
	v_cvt_f32_ubyte0_e32 v3, s1
	v_cndmask_b32_e32 v6, 0, v220, vcc
	v_sub_f32_e32 v2, v6, v2
	v_exp_f32_e32 v2, v2
	s_or_b32 s1, s0, 3
	s_add_i32 s0, s0, 4
	v_cvt_f32_ubyte0_e32 v4, s1
	v_cvt_f32_ubyte0_e32 v5, s0
	s_and_b64 s[0:1], vcc, exec
	s_cselect_b32 s0, 0xffffffc0, 0
	v_cmp_lt_f32_e32 vcc, s72, v3
	v_ldexp_f32 v34, v2, s0
	s_and_b64 s[0:1], vcc, exec
	v_cndmask_b32_e32 v2, 0, v220, vcc
	v_sub_f32_e32 v2, v2, v3
	v_exp_f32_e32 v2, v2
	s_cselect_b32 s0, 0xffffffc0, 0
	v_cmp_lt_f32_e32 vcc, s72, v4
	v_and_or_b32 v17, v211, 64, v190
	v_ldexp_f32 v35, v2, s0
	v_cndmask_b32_e32 v2, 0, v220, vcc
	v_sub_f32_e32 v2, v2, v4
	v_exp_f32_e32 v2, v2
	s_and_b64 s[0:1], vcc, exec
	s_cselect_b32 s0, 0xffffffc0, 0
	v_cmp_lt_f32_e32 vcc, s72, v5
	v_ldexp_f32 v36, v2, s0
	s_and_b64 s[0:1], vcc, exec
	v_cndmask_b32_e32 v2, 0, v220, vcc
	v_sub_f32_e32 v2, v2, v5
	v_exp_f32_e32 v2, v2
	s_cselect_b32 s0, 0xffffffc0, 0
	s_lshr_b32 s20, s81, 6
	s_add_i32 s22, s20, -1
	v_cmp_eq_u32_e64 s[4:5], s20, v32
	v_cmp_eq_u32_e64 s[6:7], s22, v32
	v_ldexp_f32 v37, v2, s0
	v_cmp_gt_u32_e64 s[0:1], 16, v106
	s_or_b64 s[4:5], s[4:5], s[6:7]
	s_or_b64 s[0:1], s[4:5], s[0:1]
	v_cmp_lt_i32_e32 vcc, s20, v32
	v_cndmask_b32_e64 v2, v14, v222, s[0:1]
	v_lshlrev_b32_e32 v17, 2, v17
	v_cndmask_b32_e32 v14, v2, v221, vcc
	v_add_u32_e32 v2, 4, v32
	v_cmp_eq_u32_e64 s[0:1], 0, v2
	v_cmp_eq_u32_e64 s[6:7], s20, v2
	s_or_b64 s[6:7], s[0:1], s[6:7]
	v_cmp_eq_u32_e64 s[0:1], s22, v2
	s_or_b64 s[0:1], s[6:7], s[0:1]
	v_cmp_lt_i32_e64 s[4:5], s20, v2
	v_cndmask_b32_e64 v3, v15, v222, s[0:1]
	ds_bpermute_b32 v18, v17, v14
	v_cndmask_b32_e64 v15, v3, v221, s[4:5]
	v_add_u32_e32 v3, 8, v32
	v_cmp_eq_u32_e64 s[0:1], 0, v3
	v_cmp_eq_u32_e64 s[8:9], s20, v3
	s_or_b64 s[8:9], s[0:1], s[8:9]
	v_cmp_eq_u32_e64 s[0:1], s22, v3
	s_or_b64 s[0:1], s[8:9], s[0:1]
	v_cmp_lt_i32_e64 s[6:7], s20, v3
	v_cndmask_b32_e64 v4, v12, v222, s[0:1]
	v_cmp_lt_i32_e64 s[24:25], -8, v32
	v_cndmask_b32_e64 v12, v4, v221, s[6:7]
	v_add_u32_e32 v4, 12, v32
	v_cmp_eq_u32_e64 s[0:1], 0, v4
	v_cmp_eq_u32_e64 s[10:11], s20, v4
	s_or_b64 s[10:11], s[0:1], s[10:11]
	v_cmp_eq_u32_e64 s[0:1], s22, v4
	s_or_b64 s[0:1], s[10:11], s[0:1]
	v_cmp_lt_i32_e64 s[8:9], s20, v4
	v_cndmask_b32_e64 v5, v13, v222, s[0:1]
	v_cmp_lt_i32_e64 s[28:29], -12, v32
	v_cndmask_b32_e64 v13, v5, v221, s[8:9]
	v_add_u32_e32 v5, 16, v32
	v_cmp_eq_u32_e64 s[0:1], 0, v5
	v_cmp_eq_u32_e64 s[12:13], s20, v5
	s_or_b64 s[12:13], s[0:1], s[12:13]
	v_cmp_eq_u32_e64 s[0:1], s22, v5
	s_or_b64 s[0:1], s[12:13], s[0:1]
	v_cmp_lt_i32_e64 s[10:11], s20, v5
	v_cndmask_b32_e64 v6, v10, v222, s[0:1]
	v_cmp_lt_i32_e64 s[34:35], -16, v32
	v_cndmask_b32_e64 v10, v6, v221, s[10:11]
	v_add_u32_e32 v6, 20, v32
	v_cmp_eq_u32_e64 s[0:1], 0, v6
	v_cmp_eq_u32_e64 s[14:15], s20, v6
	s_or_b64 s[14:15], s[0:1], s[14:15]
	v_cmp_eq_u32_e64 s[0:1], s22, v6
	s_or_b64 s[0:1], s[14:15], s[0:1]
	v_cmp_lt_i32_e64 s[12:13], s20, v6
	v_cndmask_b32_e64 v7, v11, v222, s[0:1]
	s_movk_i32 s30, 0xffe8
	v_cndmask_b32_e64 v11, v7, v221, s[12:13]
	v_add_u32_e32 v7, 24, v32
	v_cmp_eq_u32_e64 s[0:1], 0, v7
	v_cmp_eq_u32_e64 s[16:17], s20, v7
	s_or_b64 s[16:17], s[0:1], s[16:17]
	v_cmp_eq_u32_e64 s[0:1], s22, v7
	s_or_b64 s[0:1], s[16:17], s[0:1]
	v_cmp_lt_i32_e64 s[14:15], s20, v7
	v_cndmask_b32_e64 v8, v8, v222, s[0:1]
	s_waitcnt lgkmcnt(0)
	v_cmp_eq_f32_e64 s[26:27], v11, v18
	v_cndmask_b32_e64 v16, v8, v221, s[14:15]
	v_add_u32_e32 v8, 28, v32
	v_cmp_lt_i32_e64 s[16:17], s20, v8
	v_cmp_eq_u32_e64 s[0:1], 0, v8
	v_cmp_eq_u32_e64 s[20:21], s20, v8
	s_or_b64 s[20:21], s[0:1], s[20:21]
	v_cmp_eq_u32_e64 s[0:1], s22, v8
	s_or_b64 s[0:1], s[20:21], s[0:1]
	v_cmp_eq_f32_e64 s[20:21], v14, v18
	v_cndmask_b32_e64 v9, v9, v222, s[0:1]
	v_cmp_lt_f32_e64 s[0:1], v14, v18
	s_and_b64 s[20:21], s[18:19], s[20:21]
	s_or_b64 s[0:1], s[0:1], s[20:21]
	v_cmp_eq_f32_e64 s[22:23], v15, v18
	v_cmp_lt_i32_e64 s[20:21], -4, v32
	v_cndmask_b32_e64 v19, 0, 1, s[0:1]
	v_cmp_lt_f32_e64 s[0:1], v15, v18
	s_and_b64 s[22:23], s[20:21], s[22:23]
	s_or_b64 s[0:1], s[0:1], s[22:23]
	v_cmp_eq_f32_e64 s[22:23], v12, v18
	v_cndmask_b32_e64 v20, 0, 1, s[0:1]
	v_cmp_lt_f32_e64 s[0:1], v12, v18
	s_and_b64 s[22:23], s[24:25], s[22:23]
	s_or_b64 s[0:1], s[0:1], s[22:23]
	v_cmp_eq_f32_e64 s[22:23], v13, v18
	v_cndmask_b32_e64 v21, 0, 1, s[0:1]
	v_cmp_lt_f32_e64 s[0:1], v13, v18
	s_and_b64 s[22:23], s[28:29], s[22:23]
	s_or_b64 s[0:1], s[0:1], s[22:23]
	v_cmp_eq_f32_e64 s[22:23], v10, v18
	v_cndmask_b32_e64 v22, 0, 1, s[0:1]
	v_cmp_lt_f32_e64 s[0:1], v10, v18
	s_and_b64 s[22:23], s[34:35], s[22:23]
	s_or_b64 s[0:1], s[0:1], s[22:23]
	v_cndmask_b32_e64 v23, 0, 1, s[0:1]
	s_movk_i32 s0, 0xffec
	v_cmp_lt_i32_e64 s[0:1], s0, v32
	v_cmp_lt_f32_e64 s[22:23], v11, v18
	s_and_b64 s[26:27], s[0:1], s[26:27]
	s_or_b64 s[22:23], s[22:23], s[26:27]
	v_cmp_eq_f32_e64 s[26:27], v16, v18
	v_cmp_lt_i32_e64 s[30:31], s30, v32
	ds_bpermute_b32 v26, v17, v15
	v_cndmask_b32_e64 v9, v9, v221, s[16:17]
	v_cndmask_b32_e64 v24, 0, 1, s[22:23]
	v_cmp_lt_f32_e64 s[22:23], v16, v18
	s_and_b64 s[26:27], s[30:31], s[26:27]
	s_movk_i32 s36, 0xffe4
	s_or_b64 s[22:23], s[22:23], s[26:27]
	v_cmp_eq_f32_e64 s[26:27], v9, v18
	v_cmp_lt_i32_e64 s[36:37], s36, v32
	v_cndmask_b32_e64 v25, 0, 1, s[22:23]
	v_cmp_lt_f32_e64 s[22:23], v9, v18
	s_and_b64 s[26:27], s[36:37], s[26:27]
	s_or_b64 s[22:23], s[22:23], s[26:27]
	v_cndmask_b32_e64 v18, 0, 1, s[22:23]
	s_waitcnt lgkmcnt(0)
	v_cmp_eq_f32_e64 s[36:37], v14, v26
	v_cmp_lt_i32_e64 s[22:23], 4, v32
	v_cmp_lt_f32_e64 s[26:27], v14, v26
	s_and_b64 s[36:37], s[22:23], s[36:37]
	s_or_b64 s[26:27], s[26:27], s[36:37]
	v_addc_co_u32_e64 v19, s[26:27], 0, v19, s[26:27]
	v_cmp_eq_f32_e64 s[36:37], v15, v26
	v_cmp_lt_f32_e64 s[26:27], v15, v26
	s_and_b64 s[36:37], s[18:19], s[36:37]
	s_or_b64 s[26:27], s[26:27], s[36:37]
	v_cmp_eq_f32_e64 s[36:37], v12, v26
	v_cndmask_b32_e64 v27, 0, 1, s[26:27]
	v_cmp_lt_f32_e64 s[26:27], v12, v26
	s_and_b64 s[36:37], s[20:21], s[36:37]
	s_or_b64 s[26:27], s[26:27], s[36:37]
	v_addc_co_u32_e64 v21, s[26:27], 0, v21, s[26:27]
	v_cmp_eq_f32_e64 s[36:37], v13, v26
	v_cmp_lt_f32_e64 s[26:27], v13, v26
	s_and_b64 s[36:37], s[24:25], s[36:37]
	s_or_b64 s[26:27], s[26:27], s[36:37]
	v_cmp_eq_f32_e64 s[36:37], v10, v26
	v_add_u32_e32 v20, v27, v20
	v_cndmask_b32_e64 v27, 0, 1, s[26:27]
	v_cmp_lt_f32_e64 s[26:27], v10, v26
	s_and_b64 s[36:37], s[28:29], s[36:37]
	s_or_b64 s[26:27], s[26:27], s[36:37]
	v_addc_co_u32_e64 v23, s[26:27], 0, v23, s[26:27]
	v_cmp_eq_f32_e64 s[36:37], v11, v26
	v_cmp_lt_f32_e64 s[26:27], v11, v26
	s_and_b64 s[36:37], s[34:35], s[36:37]
	s_or_b64 s[26:27], s[26:27], s[36:37]
	v_cmp_eq_f32_e64 s[36:37], v16, v26
	v_cndmask_b32_e64 v28, 0, 1, s[26:27]
	v_cmp_lt_f32_e64 s[26:27], v16, v26
	s_and_b64 s[36:37], s[0:1], s[36:37]
	ds_bpermute_b32 v29, v17, v12
	s_or_b64 s[26:27], s[26:27], s[36:37]
	v_addc_co_u32_e64 v25, s[26:27], 0, v25, s[26:27]
	v_cmp_eq_f32_e64 s[36:37], v9, v26
	v_cmp_lt_f32_e64 s[26:27], v9, v26
	s_and_b64 s[30:31], s[30:31], s[36:37]
	s_or_b64 s[26:27], s[26:27], s[30:31]
	v_cndmask_b32_e64 v26, 0, 1, s[26:27]
	s_waitcnt lgkmcnt(0)
	v_cmp_eq_f32_e64 s[36:37], v14, v29
	v_cmp_lt_i32_e64 s[26:27], 8, v32
	v_cmp_lt_f32_e64 s[30:31], v14, v29
	s_and_b64 s[36:37], s[26:27], s[36:37]
	s_or_b64 s[30:31], s[30:31], s[36:37]
	v_cmp_eq_f32_e64 s[36:37], v15, v29
	v_cndmask_b32_e64 v30, 0, 1, s[30:31]
	v_cmp_lt_f32_e64 s[30:31], v15, v29
	s_and_b64 s[36:37], s[22:23], s[36:37]
	s_or_b64 s[30:31], s[30:31], s[36:37]
	v_cmp_eq_f32_e64 s[36:37], v12, v29
	v_cndmask_b32_e64 v31, 0, 1, s[30:31]
	v_cmp_lt_f32_e64 s[30:31], v12, v29
	s_and_b64 s[36:37], s[18:19], s[36:37]
	s_or_b64 s[30:31], s[30:31], s[36:37]
	v_cmp_eq_f32_e64 s[36:37], v13, v29
	v_cndmask_b32_e64 v38, 0, 1, s[30:31]
	v_cmp_lt_f32_e64 s[30:31], v13, v29
	s_and_b64 s[36:37], s[20:21], s[36:37]
	s_or_b64 s[30:31], s[30:31], s[36:37]
	v_addc_co_u32_e64 v22, s[30:31], v27, v22, s[30:31]
	v_cmp_eq_f32_e64 s[36:37], v10, v29
	v_cmp_lt_f32_e64 s[30:31], v10, v29
	s_and_b64 s[36:37], s[24:25], s[36:37]
	s_or_b64 s[30:31], s[30:31], s[36:37]
	v_cmp_eq_f32_e64 s[36:37], v11, v29
	v_cndmask_b32_e64 v27, 0, 1, s[30:31]
	v_cmp_lt_f32_e64 s[30:31], v11, v29
	s_and_b64 s[36:37], s[28:29], s[36:37]
	s_or_b64 s[30:31], s[30:31], s[36:37]
	v_addc_co_u32_e64 v24, s[30:31], v28, v24, s[30:31]
	v_cmp_eq_f32_e64 s[36:37], v16, v29
	v_cmp_lt_f32_e64 s[30:31], v16, v29
	s_and_b64 s[36:37], s[34:35], s[36:37]
	s_or_b64 s[30:31], s[30:31], s[36:37]
	v_cmp_eq_f32_e64 s[36:37], v9, v29
	v_cndmask_b32_e64 v28, 0, 1, s[30:31]
	v_cmp_lt_f32_e64 s[30:31], v9, v29
	s_and_b64 s[0:1], s[0:1], s[36:37]
	s_or_b64 s[0:1], s[30:31], s[0:1]
	v_addc_co_u32_e64 v18, s[0:1], v26, v18, s[0:1]
	ds_bpermute_b32 v26, v17, v13
	v_cmp_lt_i32_e64 s[30:31], 12, v32
	v_lshlrev_b32_e64 v2, v2, 1
	v_lshlrev_b32_e64 v3, v3, 1
	v_lshlrev_b32_e64 v4, v4, 1
	s_waitcnt lgkmcnt(0)
	v_cmp_eq_f32_e64 s[36:37], v14, v26
	v_cmp_lt_f32_e64 s[0:1], v14, v26
	s_and_b64 s[36:37], s[30:31], s[36:37]
	s_or_b64 s[0:1], s[0:1], s[36:37]
	v_addc_co_u32_e64 v19, s[0:1], v19, v30, s[0:1]
	v_cmp_eq_f32_e64 s[36:37], v15, v26
	v_cmp_lt_f32_e64 s[0:1], v15, v26
	s_and_b64 s[36:37], s[26:27], s[36:37]
	s_or_b64 s[0:1], s[0:1], s[36:37]
	v_addc_co_u32_e64 v20, s[0:1], v20, v31, s[0:1]
	v_cmp_eq_f32_e64 s[36:37], v12, v26
	v_cmp_lt_f32_e64 s[0:1], v12, v26
	s_and_b64 s[36:37], s[22:23], s[36:37]
	s_or_b64 s[0:1], s[0:1], s[36:37]
	v_addc_co_u32_e64 v21, s[0:1], v21, v38, s[0:1]
	v_cmp_eq_f32_e64 s[36:37], v13, v26
	v_cmp_lt_f32_e64 s[0:1], v13, v26
	s_and_b64 s[36:37], s[18:19], s[36:37]
	s_or_b64 s[0:1], s[0:1], s[36:37]
	v_cmp_eq_f32_e64 s[36:37], v10, v26
	v_cndmask_b32_e64 v29, 0, 1, s[0:1]
	v_cmp_lt_f32_e64 s[0:1], v10, v26
	s_and_b64 s[36:37], s[20:21], s[36:37]
	s_or_b64 s[0:1], s[0:1], s[36:37]
	v_addc_co_u32_e64 v23, s[0:1], v23, v27, s[0:1]
	v_cmp_eq_f32_e64 s[36:37], v11, v26
	v_cmp_lt_f32_e64 s[0:1], v11, v26
	s_and_b64 s[36:37], s[24:25], s[36:37]
	s_or_b64 s[0:1], s[0:1], s[36:37]
	v_cmp_eq_f32_e64 s[36:37], v16, v26
	v_cndmask_b32_e64 v27, 0, 1, s[0:1]
	v_cmp_lt_f32_e64 s[0:1], v16, v26
	s_and_b64 s[36:37], s[28:29], s[36:37]
	s_or_b64 s[0:1], s[0:1], s[36:37]
	v_addc_co_u32_e64 v25, s[0:1], v25, v28, s[0:1]
	ds_bpermute_b32 v28, v17, v10
	v_cmp_eq_f32_e64 s[36:37], v9, v26
	v_cmp_lt_f32_e64 s[0:1], v9, v26
	s_and_b64 s[34:35], s[34:35], s[36:37]
	s_or_b64 s[0:1], s[0:1], s[34:35]
	s_waitcnt lgkmcnt(0)
	v_cmp_eq_f32_e64 s[36:37], v14, v28
	v_cmp_lt_i32_e64 s[34:35], 16, v32
	v_cndmask_b32_e64 v26, 0, 1, s[0:1]
	v_cmp_lt_f32_e64 s[0:1], v14, v28
	s_and_b64 s[36:37], s[34:35], s[36:37]
	s_or_b64 s[0:1], s[0:1], s[36:37]
	v_cmp_eq_f32_e64 s[36:37], v15, v28
	v_add_u32_e32 v22, v22, v29
	v_cndmask_b32_e64 v29, 0, 1, s[0:1]
	v_cmp_lt_f32_e64 s[0:1], v15, v28
	s_and_b64 s[36:37], s[30:31], s[36:37]
	s_or_b64 s[0:1], s[0:1], s[36:37]
	v_cmp_eq_f32_e64 s[36:37], v12, v28
	v_cndmask_b32_e64 v30, 0, 1, s[0:1]
	v_cmp_lt_f32_e64 s[0:1], v12, v28
	s_and_b64 s[36:37], s[26:27], s[36:37]
	s_or_b64 s[0:1], s[0:1], s[36:37]
	v_cmp_eq_f32_e64 s[36:37], v13, v28
	v_cndmask_b32_e64 v31, 0, 1, s[0:1]
	v_cmp_lt_f32_e64 s[0:1], v13, v28
	s_and_b64 s[36:37], s[22:23], s[36:37]
	s_or_b64 s[0:1], s[0:1], s[36:37]
	v_cmp_eq_f32_e64 s[36:37], v10, v28
	v_cndmask_b32_e64 v38, 0, 1, s[0:1]
	v_cmp_lt_f32_e64 s[0:1], v10, v28
	s_and_b64 s[36:37], s[18:19], s[36:37]
	s_or_b64 s[0:1], s[0:1], s[36:37]
	v_cmp_eq_f32_e64 s[36:37], v11, v28
	v_cndmask_b32_e64 v39, 0, 1, s[0:1]
	v_cmp_lt_f32_e64 s[0:1], v11, v28
	s_and_b64 s[36:37], s[20:21], s[36:37]
	s_or_b64 s[0:1], s[0:1], s[36:37]
	v_addc_co_u32_e64 v24, s[0:1], v24, v27, s[0:1]
	v_cmp_eq_f32_e64 s[36:37], v16, v28
	v_cmp_lt_f32_e64 s[0:1], v16, v28
	s_and_b64 s[36:37], s[24:25], s[36:37]
	s_or_b64 s[0:1], s[0:1], s[36:37]
	v_cmp_eq_f32_e64 s[36:37], v9, v28
	v_cndmask_b32_e64 v27, 0, 1, s[0:1]
	v_cmp_lt_f32_e64 s[0:1], v9, v28
	s_and_b64 s[28:29], s[28:29], s[36:37]
	s_or_b64 s[0:1], s[0:1], s[28:29]
	v_addc_co_u32_e64 v18, s[0:1], v18, v26, s[0:1]
	ds_bpermute_b32 v26, v17, v11
	v_cmp_lt_i32_e64 s[0:1], 20, v32
	v_lshlrev_b64 v[0:1], 10, v[0:1]
	s_mov_b32 s38, 1
	v_lshl_add_u64 v[0:1], s[86:87], 0, v[0:1]
	s_waitcnt lgkmcnt(0)
	v_cmp_eq_f32_e64 s[36:37], v14, v26
	v_cmp_lt_f32_e64 s[28:29], v14, v26
	s_and_b64 s[36:37], s[0:1], s[36:37]
	s_or_b64 s[28:29], s[28:29], s[36:37]
	v_addc_co_u32_e64 v19, s[28:29], v19, v29, s[28:29]
	v_cmp_eq_f32_e64 s[36:37], v15, v26
	v_cmp_lt_f32_e64 s[28:29], v15, v26
	s_and_b64 s[36:37], s[34:35], s[36:37]
	s_or_b64 s[28:29], s[28:29], s[36:37]
	v_addc_co_u32_e64 v20, s[28:29], v20, v30, s[28:29]
	v_cmp_eq_f32_e64 s[36:37], v12, v26
	v_cmp_lt_f32_e64 s[28:29], v12, v26
	s_and_b64 s[36:37], s[30:31], s[36:37]
	s_or_b64 s[28:29], s[28:29], s[36:37]
	v_addc_co_u32_e64 v21, s[28:29], v21, v31, s[28:29]
	v_cmp_eq_f32_e64 s[36:37], v13, v26
	v_cmp_lt_f32_e64 s[28:29], v13, v26
	s_and_b64 s[36:37], s[26:27], s[36:37]
	s_or_b64 s[28:29], s[28:29], s[36:37]
	v_addc_co_u32_e64 v22, s[28:29], v22, v38, s[28:29]
	v_cmp_eq_f32_e64 s[36:37], v10, v26
	v_cmp_lt_f32_e64 s[28:29], v10, v26
	s_and_b64 s[36:37], s[22:23], s[36:37]
	s_or_b64 s[28:29], s[28:29], s[36:37]
	v_addc_co_u32_e64 v23, s[28:29], v23, v39, s[28:29]
	v_cmp_eq_f32_e64 s[36:37], v11, v26
	v_cmp_lt_f32_e64 s[28:29], v11, v26
	s_and_b64 s[36:37], s[18:19], s[36:37]
	s_or_b64 s[28:29], s[28:29], s[36:37]
	v_cmp_eq_f32_e64 s[36:37], v16, v26
	v_cndmask_b32_e64 v28, 0, 1, s[28:29]
	v_cmp_lt_f32_e64 s[28:29], v16, v26
	s_and_b64 s[36:37], s[20:21], s[36:37]
	s_or_b64 s[28:29], s[28:29], s[36:37]
	v_addc_co_u32_e64 v25, s[28:29], v25, v27, s[28:29]
	ds_bpermute_b32 v27, v17, v16
	v_cmp_eq_f32_e64 s[36:37], v9, v26
	v_cmp_lt_f32_e64 s[28:29], v9, v26
	s_and_b64 s[24:25], s[24:25], s[36:37]
	s_or_b64 s[24:25], s[28:29], s[24:25]
	s_waitcnt lgkmcnt(0)
	v_cmp_eq_f32_e64 s[28:29], v14, v27
	v_cmp_lt_i32_e64 s[36:37], 24, v32
	v_cndmask_b32_e64 v26, 0, 1, s[24:25]
	v_cmp_lt_f32_e64 s[24:25], v14, v27
	s_and_b64 s[28:29], s[36:37], s[28:29]
	s_or_b64 s[24:25], s[24:25], s[28:29]
	v_cmp_eq_f32_e64 s[28:29], v15, v27
	v_add_u32_e32 v24, v24, v28
	v_cndmask_b32_e64 v28, 0, 1, s[24:25]
	v_cmp_lt_f32_e64 s[24:25], v15, v27
	s_and_b64 s[28:29], s[0:1], s[28:29]
	s_or_b64 s[24:25], s[24:25], s[28:29]
	v_cmp_eq_f32_e64 s[28:29], v12, v27
	v_cndmask_b32_e64 v29, 0, 1, s[24:25]
	v_cmp_lt_f32_e64 s[24:25], v12, v27
	s_and_b64 s[28:29], s[34:35], s[28:29]
	s_or_b64 s[24:25], s[24:25], s[28:29]
	v_cmp_eq_f32_e64 s[28:29], v13, v27
	v_cndmask_b32_e64 v30, 0, 1, s[24:25]
	v_cmp_lt_f32_e64 s[24:25], v13, v27
	s_and_b64 s[28:29], s[30:31], s[28:29]
	s_or_b64 s[24:25], s[24:25], s[28:29]
	v_cmp_eq_f32_e64 s[28:29], v10, v27
	v_cndmask_b32_e64 v31, 0, 1, s[24:25]
	v_cmp_lt_f32_e64 s[24:25], v10, v27
	s_and_b64 s[28:29], s[26:27], s[28:29]
	s_or_b64 s[24:25], s[24:25], s[28:29]
	v_cmp_eq_f32_e64 s[28:29], v11, v27
	v_cndmask_b32_e64 v38, 0, 1, s[24:25]
	v_cmp_lt_f32_e64 s[24:25], v11, v27
	s_and_b64 s[28:29], s[22:23], s[28:29]
	s_or_b64 s[24:25], s[24:25], s[28:29]
	v_cmp_eq_f32_e64 s[28:29], v16, v27
	v_cndmask_b32_e64 v39, 0, 1, s[24:25]
	v_cmp_lt_f32_e64 s[24:25], v16, v27
	s_and_b64 s[28:29], s[18:19], s[28:29]
	s_or_b64 s[24:25], s[24:25], s[28:29]
	v_cmp_eq_f32_e64 s[28:29], v9, v27
	v_cndmask_b32_e64 v40, 0, 1, s[24:25]
	v_cmp_lt_f32_e64 s[24:25], v9, v27
	s_and_b64 s[20:21], s[20:21], s[28:29]
	s_or_b64 s[20:21], s[24:25], s[20:21]
	v_addc_co_u32_e64 v18, s[20:21], v18, v26, s[20:21]
	ds_bpermute_b32 v26, v17, v9
	v_cmp_lt_i32_e64 s[28:29], 28, v32
	v_ashrrev_i32_e32 v33, 31, v32
	s_waitcnt lgkmcnt(0)
	v_cmp_eq_f32_e64 s[24:25], v14, v26
	v_cmp_lt_f32_e64 s[20:21], v14, v26
	s_and_b64 s[24:25], s[28:29], s[24:25]
	s_or_b64 s[20:21], s[20:21], s[24:25]
	v_addc_co_u32_e64 v19, s[20:21], v19, v28, s[20:21]
	v_cmp_eq_f32_e64 s[24:25], v15, v26
	v_cmp_lt_f32_e64 s[20:21], v15, v26
	s_and_b64 s[24:25], s[36:37], s[24:25]
	s_or_b64 s[20:21], s[20:21], s[24:25]
	v_addc_co_u32_e64 v20, s[20:21], v20, v29, s[20:21]
	v_cmp_eq_f32_e64 s[24:25], v12, v26
	v_cmp_lt_f32_e64 s[20:21], v12, v26
	s_and_b64 s[0:1], s[0:1], s[24:25]
	s_or_b64 s[0:1], s[20:21], s[0:1]
	v_addc_co_u32_e64 v21, s[0:1], v21, v30, s[0:1]
	v_cmp_eq_f32_e64 s[20:21], v13, v26
	v_cmp_lt_f32_e64 s[0:1], v13, v26
	s_and_b64 s[20:21], s[34:35], s[20:21]
	s_or_b64 s[0:1], s[0:1], s[20:21]
	v_addc_co_u32_e64 v22, s[0:1], v22, v31, s[0:1]
	v_cmp_eq_f32_e64 s[20:21], v10, v26
	v_cmp_lt_f32_e64 s[0:1], v10, v26
	s_and_b64 s[20:21], s[30:31], s[20:21]
	s_or_b64 s[0:1], s[0:1], s[20:21]
	v_addc_co_u32_e64 v23, s[0:1], v23, v38, s[0:1]
	v_cmp_eq_f32_e64 s[20:21], v11, v26
	v_cmp_lt_f32_e64 s[0:1], v11, v26
	s_and_b64 s[20:21], s[26:27], s[20:21]
	s_or_b64 s[0:1], s[0:1], s[20:21]
	v_addc_co_u32_e64 v24, s[0:1], v24, v39, s[0:1]
	v_cmp_eq_f32_e64 s[20:21], v16, v26
	v_cmp_lt_f32_e64 s[0:1], v16, v26
	s_and_b64 s[20:21], s[22:23], s[20:21]
	s_or_b64 s[0:1], s[0:1], s[20:21]
	v_addc_co_u32_e64 v25, s[0:1], v25, v40, s[0:1]
	v_cmp_eq_f32_e64 s[20:21], v9, v26
	v_cmp_lt_f32_e64 s[0:1], v9, v26
	s_and_b64 s[18:19], s[18:19], s[20:21]
	s_or_b64 s[0:1], s[0:1], s[18:19]
	v_cndmask_b32_e64 v26, 0, 1, s[0:1]
	v_add_u32_e32 v18, v18, v26
	ds_bpermute_b32 v26, v17, v14 offset:64
	v_cmp_lt_i32_e64 s[18:19], 1, v32
	v_cmp_lt_i32_e64 s[24:25], -7, v32
	v_cmp_lt_i32_e64 s[28:29], -11, v32
	v_cmp_lt_i32_e64 s[34:35], -15, v32
	s_waitcnt lgkmcnt(0)
	v_cmp_eq_f32_e64 s[20:21], v14, v26
	v_cmp_lt_f32_e64 s[0:1], v14, v26
	s_and_b64 s[20:21], s[18:19], s[20:21]
	s_or_b64 s[0:1], s[0:1], s[20:21]
	v_cmp_eq_f32_e64 s[22:23], v15, v26
	v_cmp_lt_i32_e64 s[20:21], -3, v32
	v_cndmask_b32_e64 v27, 0, 1, s[0:1]
	v_cmp_lt_f32_e64 s[0:1], v15, v26
	s_and_b64 s[22:23], s[20:21], s[22:23]
	s_or_b64 s[0:1], s[0:1], s[22:23]
	v_cmp_eq_f32_e64 s[22:23], v12, v26
	v_cndmask_b32_e64 v28, 0, 1, s[0:1]
	v_cmp_lt_f32_e64 s[0:1], v12, v26
	s_and_b64 s[22:23], s[24:25], s[22:23]
	s_or_b64 s[0:1], s[0:1], s[22:23]
	v_cmp_eq_f32_e64 s[22:23], v13, v26
	v_cndmask_b32_e64 v29, 0, 1, s[0:1]
	v_cmp_lt_f32_e64 s[0:1], v13, v26
	s_and_b64 s[22:23], s[28:29], s[22:23]
	s_or_b64 s[0:1], s[0:1], s[22:23]
	v_cmp_eq_f32_e64 s[22:23], v10, v26
	v_cndmask_b32_e64 v30, 0, 1, s[0:1]
	v_cmp_lt_f32_e64 s[0:1], v10, v26
	s_and_b64 s[22:23], s[34:35], s[22:23]
	s_or_b64 s[0:1], s[0:1], s[22:23]
	v_cndmask_b32_e64 v31, 0, 1, s[0:1]
	s_movk_i32 s0, 0xffed
	v_cmp_eq_f32_e64 s[26:27], v11, v26
	v_cmp_lt_i32_e64 s[0:1], s0, v32
	v_cmp_lt_f32_e64 s[22:23], v11, v26
	s_and_b64 s[26:27], s[0:1], s[26:27]
	s_movk_i32 s30, 0xffe9
	s_or_b64 s[22:23], s[22:23], s[26:27]
	v_cmp_eq_f32_e64 s[26:27], v16, v26
	v_cmp_lt_i32_e64 s[30:31], s30, v32
	ds_bpermute_b32 v40, v17, v15 offset:64
	v_cndmask_b32_e64 v38, 0, 1, s[22:23]
	v_cmp_lt_f32_e64 s[22:23], v16, v26
	s_and_b64 s[26:27], s[30:31], s[26:27]
	s_movk_i32 s36, 0xffe5
	s_or_b64 s[22:23], s[22:23], s[26:27]
	v_cmp_eq_f32_e64 s[26:27], v9, v26
	v_cmp_lt_i32_e64 s[36:37], s36, v32
	v_cndmask_b32_e64 v39, 0, 1, s[22:23]
	v_cmp_lt_f32_e64 s[22:23], v9, v26
	s_and_b64 s[26:27], s[36:37], s[26:27]
	s_or_b64 s[22:23], s[22:23], s[26:27]
	v_cndmask_b32_e64 v26, 0, 1, s[22:23]
	s_waitcnt lgkmcnt(0)
	v_cmp_eq_f32_e64 s[36:37], v14, v40
	v_cmp_lt_i32_e64 s[22:23], 5, v32
	v_cmp_lt_f32_e64 s[26:27], v14, v40
	s_and_b64 s[36:37], s[22:23], s[36:37]
	s_or_b64 s[26:27], s[26:27], s[36:37]
	v_addc_co_u32_e64 v19, s[26:27], v19, v27, s[26:27]
	v_cmp_eq_f32_e64 s[36:37], v15, v40
	v_cmp_lt_f32_e64 s[26:27], v15, v40
	s_and_b64 s[36:37], s[18:19], s[36:37]
	s_or_b64 s[26:27], s[26:27], s[36:37]
	v_addc_co_u32_e64 v20, s[26:27], v20, v28, s[26:27]
	v_cmp_eq_f32_e64 s[36:37], v12, v40
	v_cmp_lt_f32_e64 s[26:27], v12, v40
	s_and_b64 s[36:37], s[20:21], s[36:37]
	s_or_b64 s[26:27], s[26:27], s[36:37]
	v_addc_co_u32_e64 v21, s[26:27], v21, v29, s[26:27]
	v_cmp_eq_f32_e64 s[36:37], v13, v40
	v_cmp_lt_f32_e64 s[26:27], v13, v40
	s_and_b64 s[36:37], s[24:25], s[36:37]
	s_or_b64 s[26:27], s[26:27], s[36:37]
	v_addc_co_u32_e64 v22, s[26:27], v22, v30, s[26:27]
	v_cmp_eq_f32_e64 s[36:37], v10, v40
	v_cmp_lt_f32_e64 s[26:27], v10, v40
	s_and_b64 s[36:37], s[28:29], s[36:37]
	s_or_b64 s[26:27], s[26:27], s[36:37]
	v_addc_co_u32_e64 v23, s[26:27], v23, v31, s[26:27]
	v_cmp_eq_f32_e64 s[36:37], v11, v40
	v_cmp_lt_f32_e64 s[26:27], v11, v40
	s_and_b64 s[36:37], s[34:35], s[36:37]
	s_or_b64 s[26:27], s[26:27], s[36:37]
	v_addc_co_u32_e64 v24, s[26:27], v24, v38, s[26:27]
	v_cmp_eq_f32_e64 s[36:37], v16, v40
	v_cmp_lt_f32_e64 s[26:27], v16, v40
	s_and_b64 s[36:37], s[0:1], s[36:37]
	s_or_b64 s[26:27], s[26:27], s[36:37]
	v_addc_co_u32_e64 v25, s[26:27], v25, v39, s[26:27]
	v_cmp_eq_f32_e64 s[36:37], v9, v40
	v_cmp_lt_f32_e64 s[26:27], v9, v40
	s_and_b64 s[30:31], s[30:31], s[36:37]
	s_or_b64 s[26:27], s[26:27], s[30:31]
	v_addc_co_u32_e64 v18, s[26:27], v18, v26, s[26:27]
	ds_bpermute_b32 v26, v17, v12 offset:64
	v_cmp_lt_i32_e64 s[26:27], 9, v32
	ds_bpermute_b32 v40, v17, v13 offset:64
	s_waitcnt lgkmcnt(1)
	v_cmp_eq_f32_e64 s[36:37], v14, v26
	v_cmp_lt_f32_e64 s[30:31], v14, v26
	s_and_b64 s[36:37], s[26:27], s[36:37]
	s_or_b64 s[30:31], s[30:31], s[36:37]
	v_cmp_eq_f32_e64 s[36:37], v15, v26
	v_cndmask_b32_e64 v27, 0, 1, s[30:31]
	v_cmp_lt_f32_e64 s[30:31], v15, v26
	s_and_b64 s[36:37], s[22:23], s[36:37]
	s_or_b64 s[30:31], s[30:31], s[36:37]
	v_cmp_eq_f32_e64 s[36:37], v12, v26
	v_cndmask_b32_e64 v28, 0, 1, s[30:31]
	v_cmp_lt_f32_e64 s[30:31], v12, v26
	s_and_b64 s[36:37], s[18:19], s[36:37]
	s_or_b64 s[30:31], s[30:31], s[36:37]
	v_cmp_eq_f32_e64 s[36:37], v13, v26
	v_cndmask_b32_e64 v29, 0, 1, s[30:31]
	v_cmp_lt_f32_e64 s[30:31], v13, v26
	s_and_b64 s[36:37], s[20:21], s[36:37]
	s_or_b64 s[30:31], s[30:31], s[36:37]
	v_cmp_eq_f32_e64 s[36:37], v10, v26
	v_cndmask_b32_e64 v30, 0, 1, s[30:31]
	v_cmp_lt_f32_e64 s[30:31], v10, v26
	s_and_b64 s[36:37], s[24:25], s[36:37]
	s_or_b64 s[30:31], s[30:31], s[36:37]
	v_cmp_eq_f32_e64 s[36:37], v11, v26
	v_cndmask_b32_e64 v31, 0, 1, s[30:31]
	v_cmp_lt_f32_e64 s[30:31], v11, v26
	s_and_b64 s[36:37], s[28:29], s[36:37]
	s_or_b64 s[30:31], s[30:31], s[36:37]
	v_cmp_eq_f32_e64 s[36:37], v16, v26
	v_cndmask_b32_e64 v38, 0, 1, s[30:31]
	v_cmp_lt_f32_e64 s[30:31], v16, v26
	s_and_b64 s[36:37], s[34:35], s[36:37]
	s_or_b64 s[30:31], s[30:31], s[36:37]
	v_cmp_eq_f32_e64 s[36:37], v9, v26
	v_cndmask_b32_e64 v39, 0, 1, s[30:31]
	v_cmp_lt_f32_e64 s[30:31], v9, v26
	s_and_b64 s[0:1], s[0:1], s[36:37]
	s_or_b64 s[0:1], s[30:31], s[0:1]
	s_waitcnt lgkmcnt(0)
	v_cmp_eq_f32_e64 s[36:37], v14, v40
	v_cmp_lt_i32_e64 s[30:31], 13, v32
	v_cndmask_b32_e64 v26, 0, 1, s[0:1]
	v_cmp_lt_f32_e64 s[0:1], v14, v40
	s_and_b64 s[36:37], s[30:31], s[36:37]
	s_or_b64 s[0:1], s[0:1], s[36:37]
	v_addc_co_u32_e64 v19, s[0:1], v19, v27, s[0:1]
	v_cmp_eq_f32_e64 s[36:37], v15, v40
	v_cmp_lt_f32_e64 s[0:1], v15, v40
	s_and_b64 s[36:37], s[26:27], s[36:37]
	s_or_b64 s[0:1], s[0:1], s[36:37]
	v_addc_co_u32_e64 v20, s[0:1], v20, v28, s[0:1]
	v_cmp_eq_f32_e64 s[36:37], v12, v40
	v_cmp_lt_f32_e64 s[0:1], v12, v40
	s_and_b64 s[36:37], s[22:23], s[36:37]
	s_or_b64 s[0:1], s[0:1], s[36:37]
	v_addc_co_u32_e64 v21, s[0:1], v21, v29, s[0:1]
	v_cmp_eq_f32_e64 s[36:37], v13, v40
	v_cmp_lt_f32_e64 s[0:1], v13, v40
	s_and_b64 s[36:37], s[18:19], s[36:37]
	s_or_b64 s[0:1], s[0:1], s[36:37]
	v_addc_co_u32_e64 v22, s[0:1], v22, v30, s[0:1]
	v_cmp_eq_f32_e64 s[36:37], v10, v40
	v_cmp_lt_f32_e64 s[0:1], v10, v40
	s_and_b64 s[36:37], s[20:21], s[36:37]
	s_or_b64 s[0:1], s[0:1], s[36:37]
	v_addc_co_u32_e64 v23, s[0:1], v23, v31, s[0:1]
	v_cmp_eq_f32_e64 s[36:37], v11, v40
	v_cmp_lt_f32_e64 s[0:1], v11, v40
	s_and_b64 s[36:37], s[24:25], s[36:37]
	s_or_b64 s[0:1], s[0:1], s[36:37]
	v_addc_co_u32_e64 v24, s[0:1], v24, v38, s[0:1]
	v_cmp_eq_f32_e64 s[36:37], v16, v40
	v_cmp_lt_f32_e64 s[0:1], v16, v40
	s_and_b64 s[36:37], s[28:29], s[36:37]
	s_or_b64 s[0:1], s[0:1], s[36:37]
	v_addc_co_u32_e64 v25, s[0:1], v25, v39, s[0:1]
	v_cmp_eq_f32_e64 s[36:37], v9, v40
	v_cmp_lt_f32_e64 s[0:1], v9, v40
	s_and_b64 s[34:35], s[34:35], s[36:37]
	s_or_b64 s[0:1], s[0:1], s[34:35]
	v_addc_co_u32_e64 v18, s[0:1], v18, v26, s[0:1]
	ds_bpermute_b32 v26, v17, v10 offset:64
	v_cmp_lt_i32_e64 s[34:35], 17, v32
	ds_bpermute_b32 v40, v17, v11 offset:64
	s_waitcnt lgkmcnt(1)
	v_cmp_eq_f32_e64 s[36:37], v14, v26
	v_cmp_lt_f32_e64 s[0:1], v14, v26
	s_and_b64 s[36:37], s[34:35], s[36:37]
	s_or_b64 s[0:1], s[0:1], s[36:37]
	v_cmp_eq_f32_e64 s[36:37], v15, v26
	v_cndmask_b32_e64 v27, 0, 1, s[0:1]
	v_cmp_lt_f32_e64 s[0:1], v15, v26
	s_and_b64 s[36:37], s[30:31], s[36:37]
	s_or_b64 s[0:1], s[0:1], s[36:37]
	v_cmp_eq_f32_e64 s[36:37], v12, v26
	v_cndmask_b32_e64 v28, 0, 1, s[0:1]
	v_cmp_lt_f32_e64 s[0:1], v12, v26
	s_and_b64 s[36:37], s[26:27], s[36:37]
	s_or_b64 s[0:1], s[0:1], s[36:37]
	v_cmp_eq_f32_e64 s[36:37], v13, v26
	v_cndmask_b32_e64 v29, 0, 1, s[0:1]
	v_cmp_lt_f32_e64 s[0:1], v13, v26
	s_and_b64 s[36:37], s[22:23], s[36:37]
	s_or_b64 s[0:1], s[0:1], s[36:37]
	v_cmp_eq_f32_e64 s[36:37], v10, v26
	v_cndmask_b32_e64 v30, 0, 1, s[0:1]
	v_cmp_lt_f32_e64 s[0:1], v10, v26
	s_and_b64 s[36:37], s[18:19], s[36:37]
	s_or_b64 s[0:1], s[0:1], s[36:37]
	v_cmp_eq_f32_e64 s[36:37], v11, v26
	v_cndmask_b32_e64 v31, 0, 1, s[0:1]
	v_cmp_lt_f32_e64 s[0:1], v11, v26
	s_and_b64 s[36:37], s[20:21], s[36:37]
	s_or_b64 s[0:1], s[0:1], s[36:37]
	v_cmp_eq_f32_e64 s[36:37], v16, v26
	v_cndmask_b32_e64 v38, 0, 1, s[0:1]
	v_cmp_lt_f32_e64 s[0:1], v16, v26
	s_and_b64 s[36:37], s[24:25], s[36:37]
	s_or_b64 s[0:1], s[0:1], s[36:37]
	v_cmp_eq_f32_e64 s[36:37], v9, v26
	v_cndmask_b32_e64 v39, 0, 1, s[0:1]
	v_cmp_lt_f32_e64 s[0:1], v9, v26
	s_and_b64 s[28:29], s[28:29], s[36:37]
	s_or_b64 s[0:1], s[0:1], s[28:29]
	v_cndmask_b32_e64 v26, 0, 1, s[0:1]
	s_waitcnt lgkmcnt(0)
	v_cmp_eq_f32_e64 s[36:37], v14, v40
	v_cmp_lt_i32_e64 s[0:1], 21, v32
	v_cmp_lt_f32_e64 s[28:29], v14, v40
	s_and_b64 s[36:37], s[0:1], s[36:37]
	s_or_b64 s[28:29], s[28:29], s[36:37]
	v_addc_co_u32_e64 v19, s[28:29], v19, v27, s[28:29]
	v_cmp_eq_f32_e64 s[36:37], v15, v40
	v_cmp_lt_f32_e64 s[28:29], v15, v40
	s_and_b64 s[36:37], s[34:35], s[36:37]
	s_or_b64 s[28:29], s[28:29], s[36:37]
	v_addc_co_u32_e64 v20, s[28:29], v20, v28, s[28:29]
	v_cmp_eq_f32_e64 s[36:37], v12, v40
	v_cmp_lt_f32_e64 s[28:29], v12, v40
	s_and_b64 s[36:37], s[30:31], s[36:37]
	s_or_b64 s[28:29], s[28:29], s[36:37]
	v_addc_co_u32_e64 v21, s[28:29], v21, v29, s[28:29]
	v_cmp_eq_f32_e64 s[36:37], v13, v40
	v_cmp_lt_f32_e64 s[28:29], v13, v40
	s_and_b64 s[36:37], s[26:27], s[36:37]
	s_or_b64 s[28:29], s[28:29], s[36:37]
	v_addc_co_u32_e64 v22, s[28:29], v22, v30, s[28:29]
	v_cmp_eq_f32_e64 s[36:37], v10, v40
	v_cmp_lt_f32_e64 s[28:29], v10, v40
	s_and_b64 s[36:37], s[22:23], s[36:37]
	s_or_b64 s[28:29], s[28:29], s[36:37]
	v_addc_co_u32_e64 v23, s[28:29], v23, v31, s[28:29]
	v_cmp_eq_f32_e64 s[36:37], v11, v40
	v_cmp_lt_f32_e64 s[28:29], v11, v40
	s_and_b64 s[36:37], s[18:19], s[36:37]
	s_or_b64 s[28:29], s[28:29], s[36:37]
	v_addc_co_u32_e64 v24, s[28:29], v24, v38, s[28:29]
	v_cmp_eq_f32_e64 s[36:37], v16, v40
	v_cmp_lt_f32_e64 s[28:29], v16, v40
	s_and_b64 s[36:37], s[20:21], s[36:37]
	s_or_b64 s[28:29], s[28:29], s[36:37]
	v_addc_co_u32_e64 v25, s[28:29], v25, v39, s[28:29]
	v_cmp_eq_f32_e64 s[36:37], v9, v40
	v_cmp_lt_f32_e64 s[28:29], v9, v40
	s_and_b64 s[24:25], s[24:25], s[36:37]
	s_or_b64 s[24:25], s[28:29], s[24:25]
	v_addc_co_u32_e64 v18, s[24:25], v18, v26, s[24:25]
	ds_bpermute_b32 v26, v17, v16 offset:64
	v_cmp_lt_i32_e64 s[36:37], 25, v32
	ds_bpermute_b32 v40, v17, v9 offset:64
	s_waitcnt lgkmcnt(1)
	v_cmp_eq_f32_e64 s[28:29], v14, v26
	v_cmp_lt_f32_e64 s[24:25], v14, v26
	s_and_b64 s[28:29], s[36:37], s[28:29]
	s_or_b64 s[24:25], s[24:25], s[28:29]
	v_cmp_eq_f32_e64 s[28:29], v15, v26
	v_cndmask_b32_e64 v27, 0, 1, s[24:25]
	v_cmp_lt_f32_e64 s[24:25], v15, v26
	s_and_b64 s[28:29], s[0:1], s[28:29]
	s_or_b64 s[24:25], s[24:25], s[28:29]
	v_cmp_eq_f32_e64 s[28:29], v12, v26
	v_cndmask_b32_e64 v28, 0, 1, s[24:25]
	v_cmp_lt_f32_e64 s[24:25], v12, v26
	s_and_b64 s[28:29], s[34:35], s[28:29]
	s_or_b64 s[24:25], s[24:25], s[28:29]
	v_cmp_eq_f32_e64 s[28:29], v13, v26
	v_cndmask_b32_e64 v29, 0, 1, s[24:25]
	v_cmp_lt_f32_e64 s[24:25], v13, v26
	s_and_b64 s[28:29], s[30:31], s[28:29]
	s_or_b64 s[24:25], s[24:25], s[28:29]
	v_cmp_eq_f32_e64 s[28:29], v10, v26
	v_cndmask_b32_e64 v30, 0, 1, s[24:25]
	v_cmp_lt_f32_e64 s[24:25], v10, v26
	s_and_b64 s[28:29], s[26:27], s[28:29]
	s_or_b64 s[24:25], s[24:25], s[28:29]
	v_cmp_eq_f32_e64 s[28:29], v11, v26
	v_cndmask_b32_e64 v31, 0, 1, s[24:25]
	v_cmp_lt_f32_e64 s[24:25], v11, v26
	s_and_b64 s[28:29], s[22:23], s[28:29]
	s_or_b64 s[24:25], s[24:25], s[28:29]
	v_cmp_eq_f32_e64 s[28:29], v16, v26
	v_cndmask_b32_e64 v38, 0, 1, s[24:25]
	v_cmp_lt_f32_e64 s[24:25], v16, v26
	s_and_b64 s[28:29], s[18:19], s[28:29]
	s_or_b64 s[24:25], s[24:25], s[28:29]
	v_cmp_eq_f32_e64 s[28:29], v9, v26
	v_cndmask_b32_e64 v39, 0, 1, s[24:25]
	v_cmp_lt_f32_e64 s[24:25], v9, v26
	s_and_b64 s[20:21], s[20:21], s[28:29]
	s_or_b64 s[20:21], s[24:25], s[20:21]
	s_waitcnt lgkmcnt(0)
	v_cmp_eq_f32_e64 s[24:25], v14, v40
	v_cmp_lt_i32_e64 s[28:29], 29, v32
	v_cndmask_b32_e64 v26, 0, 1, s[20:21]
	v_cmp_lt_f32_e64 s[20:21], v14, v40
	s_and_b64 s[24:25], s[28:29], s[24:25]
	s_or_b64 s[20:21], s[20:21], s[24:25]
	v_addc_co_u32_e64 v19, s[20:21], v19, v27, s[20:21]
	v_cmp_eq_f32_e64 s[24:25], v15, v40
	v_cmp_lt_f32_e64 s[20:21], v15, v40
	s_and_b64 s[24:25], s[36:37], s[24:25]
	s_or_b64 s[20:21], s[20:21], s[24:25]
	v_addc_co_u32_e64 v20, s[20:21], v20, v28, s[20:21]
	v_cmp_eq_f32_e64 s[24:25], v12, v40
	v_cmp_lt_f32_e64 s[20:21], v12, v40
	s_and_b64 s[0:1], s[0:1], s[24:25]
	s_or_b64 s[0:1], s[20:21], s[0:1]
	v_addc_co_u32_e64 v21, s[0:1], v21, v29, s[0:1]
	v_cmp_eq_f32_e64 s[20:21], v13, v40
	v_cmp_lt_f32_e64 s[0:1], v13, v40
	s_and_b64 s[20:21], s[34:35], s[20:21]
	s_or_b64 s[0:1], s[0:1], s[20:21]
	v_addc_co_u32_e64 v22, s[0:1], v22, v30, s[0:1]
	v_cmp_eq_f32_e64 s[20:21], v10, v40
	v_cmp_lt_f32_e64 s[0:1], v10, v40
	s_and_b64 s[20:21], s[30:31], s[20:21]
	s_or_b64 s[0:1], s[0:1], s[20:21]
	v_addc_co_u32_e64 v23, s[0:1], v23, v31, s[0:1]
	v_cmp_eq_f32_e64 s[20:21], v11, v40
	v_cmp_lt_f32_e64 s[0:1], v11, v40
	s_and_b64 s[20:21], s[26:27], s[20:21]
	s_or_b64 s[0:1], s[0:1], s[20:21]
	v_addc_co_u32_e64 v24, s[0:1], v24, v38, s[0:1]
	v_cmp_eq_f32_e64 s[20:21], v16, v40
	v_cmp_lt_f32_e64 s[0:1], v16, v40
	s_and_b64 s[20:21], s[22:23], s[20:21]
	s_or_b64 s[0:1], s[0:1], s[20:21]
	v_addc_co_u32_e64 v25, s[0:1], v25, v39, s[0:1]
	v_cmp_eq_f32_e64 s[20:21], v9, v40
	v_cmp_lt_f32_e64 s[0:1], v9, v40
	s_and_b64 s[18:19], s[18:19], s[20:21]
	s_or_b64 s[0:1], s[0:1], s[18:19]
	v_addc_co_u32_e64 v18, s[0:1], v18, v26, s[0:1]
	ds_bpermute_b32 v26, v17, v14 offset:128
	v_cmp_lt_i32_e64 s[18:19], 2, v32
	v_cmp_lt_i32_e64 s[24:25], -6, v32
	v_cmp_lt_i32_e64 s[28:29], -10, v32
	v_cmp_lt_i32_e64 s[34:35], -14, v32
	s_waitcnt lgkmcnt(0)
	v_cmp_eq_f32_e64 s[20:21], v14, v26
	v_cmp_lt_f32_e64 s[0:1], v14, v26
	s_and_b64 s[20:21], s[18:19], s[20:21]
	s_or_b64 s[0:1], s[0:1], s[20:21]
	v_cmp_eq_f32_e64 s[22:23], v15, v26
	v_cmp_lt_i32_e64 s[20:21], -2, v32
	v_cndmask_b32_e64 v27, 0, 1, s[0:1]
	v_cmp_lt_f32_e64 s[0:1], v15, v26
	s_and_b64 s[22:23], s[20:21], s[22:23]
	s_or_b64 s[0:1], s[0:1], s[22:23]
	v_cmp_eq_f32_e64 s[22:23], v12, v26
	v_cndmask_b32_e64 v28, 0, 1, s[0:1]
	v_cmp_lt_f32_e64 s[0:1], v12, v26
	s_and_b64 s[22:23], s[24:25], s[22:23]
	s_or_b64 s[0:1], s[0:1], s[22:23]
	v_cmp_eq_f32_e64 s[22:23], v13, v26
	v_cndmask_b32_e64 v29, 0, 1, s[0:1]
	v_cmp_lt_f32_e64 s[0:1], v13, v26
	s_and_b64 s[22:23], s[28:29], s[22:23]
	s_or_b64 s[0:1], s[0:1], s[22:23]
	v_cmp_eq_f32_e64 s[22:23], v10, v26
	v_cndmask_b32_e64 v30, 0, 1, s[0:1]
	v_cmp_lt_f32_e64 s[0:1], v10, v26
	s_and_b64 s[22:23], s[34:35], s[22:23]
	s_or_b64 s[0:1], s[0:1], s[22:23]
	v_cndmask_b32_e64 v31, 0, 1, s[0:1]
	s_movk_i32 s0, 0xffee
	v_cmp_eq_f32_e64 s[26:27], v11, v26
	v_cmp_lt_i32_e64 s[0:1], s0, v32
	v_cmp_lt_f32_e64 s[22:23], v11, v26
	s_and_b64 s[26:27], s[0:1], s[26:27]
	s_movk_i32 s30, 0xffea
	s_or_b64 s[22:23], s[22:23], s[26:27]
	v_cmp_eq_f32_e64 s[26:27], v16, v26
	v_cmp_lt_i32_e64 s[30:31], s30, v32
	ds_bpermute_b32 v40, v17, v15 offset:128
	v_cndmask_b32_e64 v38, 0, 1, s[22:23]
	v_cmp_lt_f32_e64 s[22:23], v16, v26
	s_and_b64 s[26:27], s[30:31], s[26:27]
	s_movk_i32 s36, 0xffe6
	s_or_b64 s[22:23], s[22:23], s[26:27]
	v_cmp_eq_f32_e64 s[26:27], v9, v26
	v_cmp_lt_i32_e64 s[36:37], s36, v32
	v_cndmask_b32_e64 v39, 0, 1, s[22:23]
	v_cmp_lt_f32_e64 s[22:23], v9, v26
	s_and_b64 s[26:27], s[36:37], s[26:27]
	s_or_b64 s[22:23], s[22:23], s[26:27]
	v_cndmask_b32_e64 v26, 0, 1, s[22:23]
	s_waitcnt lgkmcnt(0)
	v_cmp_eq_f32_e64 s[36:37], v14, v40
	v_cmp_lt_i32_e64 s[22:23], 6, v32
	v_cmp_lt_f32_e64 s[26:27], v14, v40
	s_and_b64 s[36:37], s[22:23], s[36:37]
	s_or_b64 s[26:27], s[26:27], s[36:37]
	v_addc_co_u32_e64 v19, s[26:27], v19, v27, s[26:27]
	v_cmp_eq_f32_e64 s[36:37], v15, v40
	v_cmp_lt_f32_e64 s[26:27], v15, v40
	s_and_b64 s[36:37], s[18:19], s[36:37]
	s_or_b64 s[26:27], s[26:27], s[36:37]
	v_addc_co_u32_e64 v20, s[26:27], v20, v28, s[26:27]
	v_cmp_eq_f32_e64 s[36:37], v12, v40
	v_cmp_lt_f32_e64 s[26:27], v12, v40
	s_and_b64 s[36:37], s[20:21], s[36:37]
	s_or_b64 s[26:27], s[26:27], s[36:37]
	v_addc_co_u32_e64 v21, s[26:27], v21, v29, s[26:27]
	v_cmp_eq_f32_e64 s[36:37], v13, v40
	v_cmp_lt_f32_e64 s[26:27], v13, v40
	s_and_b64 s[36:37], s[24:25], s[36:37]
	s_or_b64 s[26:27], s[26:27], s[36:37]
	v_addc_co_u32_e64 v22, s[26:27], v22, v30, s[26:27]
	v_cmp_eq_f32_e64 s[36:37], v10, v40
	v_cmp_lt_f32_e64 s[26:27], v10, v40
	s_and_b64 s[36:37], s[28:29], s[36:37]
	s_or_b64 s[26:27], s[26:27], s[36:37]
	v_addc_co_u32_e64 v23, s[26:27], v23, v31, s[26:27]
	v_cmp_eq_f32_e64 s[36:37], v11, v40
	v_cmp_lt_f32_e64 s[26:27], v11, v40
	s_and_b64 s[36:37], s[34:35], s[36:37]
	s_or_b64 s[26:27], s[26:27], s[36:37]
	v_addc_co_u32_e64 v24, s[26:27], v24, v38, s[26:27]
	v_cmp_eq_f32_e64 s[36:37], v16, v40
	v_cmp_lt_f32_e64 s[26:27], v16, v40
	s_and_b64 s[36:37], s[0:1], s[36:37]
	s_or_b64 s[26:27], s[26:27], s[36:37]
	v_addc_co_u32_e64 v25, s[26:27], v25, v39, s[26:27]
	v_cmp_eq_f32_e64 s[36:37], v9, v40
	v_cmp_lt_f32_e64 s[26:27], v9, v40
	s_and_b64 s[30:31], s[30:31], s[36:37]
	s_or_b64 s[26:27], s[26:27], s[30:31]
	v_addc_co_u32_e64 v18, s[26:27], v18, v26, s[26:27]
	ds_bpermute_b32 v26, v17, v12 offset:128
	v_cmp_lt_i32_e64 s[26:27], 10, v32
	ds_bpermute_b32 v40, v17, v13 offset:128
	s_waitcnt lgkmcnt(1)
	v_cmp_eq_f32_e64 s[36:37], v14, v26
	v_cmp_lt_f32_e64 s[30:31], v14, v26
	s_and_b64 s[36:37], s[26:27], s[36:37]
	s_or_b64 s[30:31], s[30:31], s[36:37]
	v_cmp_eq_f32_e64 s[36:37], v15, v26
	v_cndmask_b32_e64 v27, 0, 1, s[30:31]
	v_cmp_lt_f32_e64 s[30:31], v15, v26
	s_and_b64 s[36:37], s[22:23], s[36:37]
	s_or_b64 s[30:31], s[30:31], s[36:37]
	v_cmp_eq_f32_e64 s[36:37], v12, v26
	v_cndmask_b32_e64 v28, 0, 1, s[30:31]
	v_cmp_lt_f32_e64 s[30:31], v12, v26
	s_and_b64 s[36:37], s[18:19], s[36:37]
	s_or_b64 s[30:31], s[30:31], s[36:37]
	v_cmp_eq_f32_e64 s[36:37], v13, v26
	v_cndmask_b32_e64 v29, 0, 1, s[30:31]
	v_cmp_lt_f32_e64 s[30:31], v13, v26
	s_and_b64 s[36:37], s[20:21], s[36:37]
	s_or_b64 s[30:31], s[30:31], s[36:37]
	v_cmp_eq_f32_e64 s[36:37], v10, v26
	v_cndmask_b32_e64 v30, 0, 1, s[30:31]
	v_cmp_lt_f32_e64 s[30:31], v10, v26
	s_and_b64 s[36:37], s[24:25], s[36:37]
	s_or_b64 s[30:31], s[30:31], s[36:37]
	v_cmp_eq_f32_e64 s[36:37], v11, v26
	v_cndmask_b32_e64 v31, 0, 1, s[30:31]
	v_cmp_lt_f32_e64 s[30:31], v11, v26
	s_and_b64 s[36:37], s[28:29], s[36:37]
	s_or_b64 s[30:31], s[30:31], s[36:37]
	v_cmp_eq_f32_e64 s[36:37], v16, v26
	v_cndmask_b32_e64 v38, 0, 1, s[30:31]
	v_cmp_lt_f32_e64 s[30:31], v16, v26
	s_and_b64 s[36:37], s[34:35], s[36:37]
	s_or_b64 s[30:31], s[30:31], s[36:37]
	v_cmp_eq_f32_e64 s[36:37], v9, v26
	v_cndmask_b32_e64 v39, 0, 1, s[30:31]
	v_cmp_lt_f32_e64 s[30:31], v9, v26
	s_and_b64 s[0:1], s[0:1], s[36:37]
	s_or_b64 s[0:1], s[30:31], s[0:1]
	s_waitcnt lgkmcnt(0)
	v_cmp_eq_f32_e64 s[36:37], v14, v40
	v_cmp_lt_i32_e64 s[30:31], 14, v32
	v_cndmask_b32_e64 v26, 0, 1, s[0:1]
	v_cmp_lt_f32_e64 s[0:1], v14, v40
	s_and_b64 s[36:37], s[30:31], s[36:37]
	s_or_b64 s[0:1], s[0:1], s[36:37]
	v_addc_co_u32_e64 v19, s[0:1], v19, v27, s[0:1]
	v_cmp_eq_f32_e64 s[36:37], v15, v40
	v_cmp_lt_f32_e64 s[0:1], v15, v40
	s_and_b64 s[36:37], s[26:27], s[36:37]
	s_or_b64 s[0:1], s[0:1], s[36:37]
	v_addc_co_u32_e64 v20, s[0:1], v20, v28, s[0:1]
	v_cmp_eq_f32_e64 s[36:37], v12, v40
	v_cmp_lt_f32_e64 s[0:1], v12, v40
	s_and_b64 s[36:37], s[22:23], s[36:37]
	s_or_b64 s[0:1], s[0:1], s[36:37]
	v_addc_co_u32_e64 v21, s[0:1], v21, v29, s[0:1]
	v_cmp_eq_f32_e64 s[36:37], v13, v40
	v_cmp_lt_f32_e64 s[0:1], v13, v40
	s_and_b64 s[36:37], s[18:19], s[36:37]
	s_or_b64 s[0:1], s[0:1], s[36:37]
	v_addc_co_u32_e64 v22, s[0:1], v22, v30, s[0:1]
	v_cmp_eq_f32_e64 s[36:37], v10, v40
	v_cmp_lt_f32_e64 s[0:1], v10, v40
	s_and_b64 s[36:37], s[20:21], s[36:37]
	s_or_b64 s[0:1], s[0:1], s[36:37]
	v_addc_co_u32_e64 v23, s[0:1], v23, v31, s[0:1]
	v_cmp_eq_f32_e64 s[36:37], v11, v40
	v_cmp_lt_f32_e64 s[0:1], v11, v40
	s_and_b64 s[36:37], s[24:25], s[36:37]
	s_or_b64 s[0:1], s[0:1], s[36:37]
	v_addc_co_u32_e64 v24, s[0:1], v24, v38, s[0:1]
	v_cmp_eq_f32_e64 s[36:37], v16, v40
	v_cmp_lt_f32_e64 s[0:1], v16, v40
	s_and_b64 s[36:37], s[28:29], s[36:37]
	s_or_b64 s[0:1], s[0:1], s[36:37]
	v_addc_co_u32_e64 v25, s[0:1], v25, v39, s[0:1]
	v_cmp_eq_f32_e64 s[36:37], v9, v40
	v_cmp_lt_f32_e64 s[0:1], v9, v40
	s_and_b64 s[34:35], s[34:35], s[36:37]
	s_or_b64 s[0:1], s[0:1], s[34:35]
	v_addc_co_u32_e64 v18, s[0:1], v18, v26, s[0:1]
	ds_bpermute_b32 v26, v17, v10 offset:128
	v_cmp_lt_i32_e64 s[34:35], 18, v32
	ds_bpermute_b32 v40, v17, v11 offset:128
	s_waitcnt lgkmcnt(1)
	v_cmp_eq_f32_e64 s[36:37], v14, v26
	v_cmp_lt_f32_e64 s[0:1], v14, v26
	s_and_b64 s[36:37], s[34:35], s[36:37]
	s_or_b64 s[0:1], s[0:1], s[36:37]
	v_cmp_eq_f32_e64 s[36:37], v15, v26
	v_cndmask_b32_e64 v27, 0, 1, s[0:1]
	v_cmp_lt_f32_e64 s[0:1], v15, v26
	s_and_b64 s[36:37], s[30:31], s[36:37]
	s_or_b64 s[0:1], s[0:1], s[36:37]
	v_cmp_eq_f32_e64 s[36:37], v12, v26
	v_cndmask_b32_e64 v28, 0, 1, s[0:1]
	v_cmp_lt_f32_e64 s[0:1], v12, v26
	s_and_b64 s[36:37], s[26:27], s[36:37]
	s_or_b64 s[0:1], s[0:1], s[36:37]
	v_cmp_eq_f32_e64 s[36:37], v13, v26
	v_cndmask_b32_e64 v29, 0, 1, s[0:1]
	v_cmp_lt_f32_e64 s[0:1], v13, v26
	s_and_b64 s[36:37], s[22:23], s[36:37]
	s_or_b64 s[0:1], s[0:1], s[36:37]
	v_cmp_eq_f32_e64 s[36:37], v10, v26
	v_cndmask_b32_e64 v30, 0, 1, s[0:1]
	v_cmp_lt_f32_e64 s[0:1], v10, v26
	s_and_b64 s[36:37], s[18:19], s[36:37]
	s_or_b64 s[0:1], s[0:1], s[36:37]
	v_cmp_eq_f32_e64 s[36:37], v11, v26
	v_cndmask_b32_e64 v31, 0, 1, s[0:1]
	v_cmp_lt_f32_e64 s[0:1], v11, v26
	s_and_b64 s[36:37], s[20:21], s[36:37]
	s_or_b64 s[0:1], s[0:1], s[36:37]
	v_cmp_eq_f32_e64 s[36:37], v16, v26
	v_cndmask_b32_e64 v38, 0, 1, s[0:1]
	v_cmp_lt_f32_e64 s[0:1], v16, v26
	s_and_b64 s[36:37], s[24:25], s[36:37]
	s_or_b64 s[0:1], s[0:1], s[36:37]
	v_cmp_eq_f32_e64 s[36:37], v9, v26
	v_cndmask_b32_e64 v39, 0, 1, s[0:1]
	v_cmp_lt_f32_e64 s[0:1], v9, v26
	s_and_b64 s[28:29], s[28:29], s[36:37]
	s_or_b64 s[0:1], s[0:1], s[28:29]
	v_cndmask_b32_e64 v26, 0, 1, s[0:1]
	s_waitcnt lgkmcnt(0)
	v_cmp_eq_f32_e64 s[36:37], v14, v40
	v_cmp_lt_i32_e64 s[0:1], 22, v32
	v_cmp_lt_f32_e64 s[28:29], v14, v40
	s_and_b64 s[36:37], s[0:1], s[36:37]
	s_or_b64 s[28:29], s[28:29], s[36:37]
	v_addc_co_u32_e64 v19, s[28:29], v19, v27, s[28:29]
	v_cmp_eq_f32_e64 s[36:37], v15, v40
	v_cmp_lt_f32_e64 s[28:29], v15, v40
	s_and_b64 s[36:37], s[34:35], s[36:37]
	s_or_b64 s[28:29], s[28:29], s[36:37]
	v_addc_co_u32_e64 v20, s[28:29], v20, v28, s[28:29]
	v_cmp_eq_f32_e64 s[36:37], v12, v40
	v_cmp_lt_f32_e64 s[28:29], v12, v40
	s_and_b64 s[36:37], s[30:31], s[36:37]
	s_or_b64 s[28:29], s[28:29], s[36:37]
	v_addc_co_u32_e64 v21, s[28:29], v21, v29, s[28:29]
	v_cmp_eq_f32_e64 s[36:37], v13, v40
	v_cmp_lt_f32_e64 s[28:29], v13, v40
	s_and_b64 s[36:37], s[26:27], s[36:37]
	s_or_b64 s[28:29], s[28:29], s[36:37]
	v_addc_co_u32_e64 v22, s[28:29], v22, v30, s[28:29]
	v_cmp_eq_f32_e64 s[36:37], v10, v40
	v_cmp_lt_f32_e64 s[28:29], v10, v40
	s_and_b64 s[36:37], s[22:23], s[36:37]
	s_or_b64 s[28:29], s[28:29], s[36:37]
	v_addc_co_u32_e64 v23, s[28:29], v23, v31, s[28:29]
	v_cmp_eq_f32_e64 s[36:37], v11, v40
	v_cmp_lt_f32_e64 s[28:29], v11, v40
	s_and_b64 s[36:37], s[18:19], s[36:37]
	s_or_b64 s[28:29], s[28:29], s[36:37]
	v_addc_co_u32_e64 v24, s[28:29], v24, v38, s[28:29]
	v_cmp_eq_f32_e64 s[36:37], v16, v40
	v_cmp_lt_f32_e64 s[28:29], v16, v40
	s_and_b64 s[36:37], s[20:21], s[36:37]
	s_or_b64 s[28:29], s[28:29], s[36:37]
	v_addc_co_u32_e64 v25, s[28:29], v25, v39, s[28:29]
	v_cmp_eq_f32_e64 s[36:37], v9, v40
	v_cmp_lt_f32_e64 s[28:29], v9, v40
	s_and_b64 s[24:25], s[24:25], s[36:37]
	s_or_b64 s[24:25], s[28:29], s[24:25]
	v_addc_co_u32_e64 v18, s[24:25], v18, v26, s[24:25]
	ds_bpermute_b32 v26, v17, v16 offset:128
	v_cmp_lt_i32_e64 s[36:37], 26, v32
	ds_bpermute_b32 v40, v17, v9 offset:128
	s_waitcnt lgkmcnt(1)
	v_cmp_eq_f32_e64 s[28:29], v14, v26
	v_cmp_lt_f32_e64 s[24:25], v14, v26
	s_and_b64 s[28:29], s[36:37], s[28:29]
	s_or_b64 s[24:25], s[24:25], s[28:29]
	v_cmp_eq_f32_e64 s[28:29], v15, v26
	v_cndmask_b32_e64 v27, 0, 1, s[24:25]
	v_cmp_lt_f32_e64 s[24:25], v15, v26
	s_and_b64 s[28:29], s[0:1], s[28:29]
	s_or_b64 s[24:25], s[24:25], s[28:29]
	v_cmp_eq_f32_e64 s[28:29], v12, v26
	v_cndmask_b32_e64 v28, 0, 1, s[24:25]
	v_cmp_lt_f32_e64 s[24:25], v12, v26
	s_and_b64 s[28:29], s[34:35], s[28:29]
	s_or_b64 s[24:25], s[24:25], s[28:29]
	v_cmp_eq_f32_e64 s[28:29], v13, v26
	v_cndmask_b32_e64 v29, 0, 1, s[24:25]
	v_cmp_lt_f32_e64 s[24:25], v13, v26
	s_and_b64 s[28:29], s[30:31], s[28:29]
	s_or_b64 s[24:25], s[24:25], s[28:29]
	v_cmp_eq_f32_e64 s[28:29], v10, v26
	v_cndmask_b32_e64 v30, 0, 1, s[24:25]
	v_cmp_lt_f32_e64 s[24:25], v10, v26
	s_and_b64 s[28:29], s[26:27], s[28:29]
	s_or_b64 s[24:25], s[24:25], s[28:29]
	v_cmp_eq_f32_e64 s[28:29], v11, v26
	v_cndmask_b32_e64 v31, 0, 1, s[24:25]
	v_cmp_lt_f32_e64 s[24:25], v11, v26
	s_and_b64 s[28:29], s[22:23], s[28:29]
	s_or_b64 s[24:25], s[24:25], s[28:29]
	v_cmp_eq_f32_e64 s[28:29], v16, v26
	v_cndmask_b32_e64 v38, 0, 1, s[24:25]
	v_cmp_lt_f32_e64 s[24:25], v16, v26
	s_and_b64 s[28:29], s[18:19], s[28:29]
	s_or_b64 s[24:25], s[24:25], s[28:29]
	v_cmp_eq_f32_e64 s[28:29], v9, v26
	v_cndmask_b32_e64 v39, 0, 1, s[24:25]
	v_cmp_lt_f32_e64 s[24:25], v9, v26
	s_and_b64 s[20:21], s[20:21], s[28:29]
	s_or_b64 s[20:21], s[24:25], s[20:21]
	s_waitcnt lgkmcnt(0)
	v_cmp_eq_f32_e64 s[24:25], v14, v40
	v_cmp_lt_i32_e64 s[28:29], 30, v32
	v_cndmask_b32_e64 v26, 0, 1, s[20:21]
	v_cmp_lt_f32_e64 s[20:21], v14, v40
	s_and_b64 s[24:25], s[28:29], s[24:25]
	s_or_b64 s[20:21], s[20:21], s[24:25]
	v_addc_co_u32_e64 v19, s[20:21], v19, v27, s[20:21]
	v_cmp_eq_f32_e64 s[24:25], v15, v40
	v_cmp_lt_f32_e64 s[20:21], v15, v40
	s_and_b64 s[24:25], s[36:37], s[24:25]
	s_or_b64 s[20:21], s[20:21], s[24:25]
	v_addc_co_u32_e64 v20, s[20:21], v20, v28, s[20:21]
	v_cmp_eq_f32_e64 s[24:25], v12, v40
	v_cmp_lt_f32_e64 s[20:21], v12, v40
	s_and_b64 s[0:1], s[0:1], s[24:25]
	s_or_b64 s[0:1], s[20:21], s[0:1]
	v_addc_co_u32_e64 v21, s[0:1], v21, v29, s[0:1]
	v_cmp_eq_f32_e64 s[20:21], v13, v40
	v_cmp_lt_f32_e64 s[0:1], v13, v40
	s_and_b64 s[20:21], s[34:35], s[20:21]
	s_or_b64 s[0:1], s[0:1], s[20:21]
	v_addc_co_u32_e64 v22, s[0:1], v22, v30, s[0:1]
	v_cmp_eq_f32_e64 s[20:21], v10, v40
	v_cmp_lt_f32_e64 s[0:1], v10, v40
	s_and_b64 s[20:21], s[30:31], s[20:21]
	s_or_b64 s[0:1], s[0:1], s[20:21]
	v_addc_co_u32_e64 v23, s[0:1], v23, v31, s[0:1]
	v_cmp_eq_f32_e64 s[20:21], v11, v40
	v_cmp_lt_f32_e64 s[0:1], v11, v40
	s_and_b64 s[20:21], s[26:27], s[20:21]
	s_or_b64 s[0:1], s[0:1], s[20:21]
	v_addc_co_u32_e64 v24, s[0:1], v24, v38, s[0:1]
	v_cmp_eq_f32_e64 s[20:21], v16, v40
	v_cmp_lt_f32_e64 s[0:1], v16, v40
	s_and_b64 s[20:21], s[22:23], s[20:21]
	s_or_b64 s[0:1], s[0:1], s[20:21]
	v_addc_co_u32_e64 v25, s[0:1], v25, v39, s[0:1]
	v_cmp_eq_f32_e64 s[20:21], v9, v40
	v_cmp_lt_f32_e64 s[0:1], v9, v40
	s_and_b64 s[18:19], s[18:19], s[20:21]
	s_or_b64 s[0:1], s[0:1], s[18:19]
	v_addc_co_u32_e64 v18, s[0:1], v18, v26, s[0:1]
	ds_bpermute_b32 v26, v17, v14 offset:192
	v_cmp_lt_i32_e64 s[18:19], 3, v32
	v_cmp_lt_i32_e64 s[24:25], -5, v32
	v_cmp_lt_i32_e64 s[28:29], -9, v32
	v_cmp_lt_i32_e64 s[34:35], -13, v32
	s_waitcnt lgkmcnt(0)
	v_cmp_eq_f32_e64 s[20:21], v14, v26
	v_cmp_lt_f32_e64 s[0:1], v14, v26
	s_and_b64 s[20:21], s[18:19], s[20:21]
	s_or_b64 s[0:1], s[0:1], s[20:21]
	v_cmp_eq_f32_e64 s[22:23], v15, v26
	v_cmp_lt_i32_e64 s[20:21], -1, v32
	v_cndmask_b32_e64 v27, 0, 1, s[0:1]
	v_cmp_lt_f32_e64 s[0:1], v15, v26
	s_and_b64 s[22:23], s[20:21], s[22:23]
	s_or_b64 s[0:1], s[0:1], s[22:23]
	v_cmp_eq_f32_e64 s[22:23], v12, v26
	v_cndmask_b32_e64 v28, 0, 1, s[0:1]
	v_cmp_lt_f32_e64 s[0:1], v12, v26
	s_and_b64 s[22:23], s[24:25], s[22:23]
	s_or_b64 s[0:1], s[0:1], s[22:23]
	v_cmp_eq_f32_e64 s[22:23], v13, v26
	v_cndmask_b32_e64 v29, 0, 1, s[0:1]
	v_cmp_lt_f32_e64 s[0:1], v13, v26
	s_and_b64 s[22:23], s[28:29], s[22:23]
	s_or_b64 s[0:1], s[0:1], s[22:23]
	v_cmp_eq_f32_e64 s[22:23], v10, v26
	v_cndmask_b32_e64 v30, 0, 1, s[0:1]
	v_cmp_lt_f32_e64 s[0:1], v10, v26
	s_and_b64 s[22:23], s[34:35], s[22:23]
	s_or_b64 s[0:1], s[0:1], s[22:23]
	v_cndmask_b32_e64 v31, 0, 1, s[0:1]
	s_movk_i32 s0, 0xffef
	v_cmp_eq_f32_e64 s[26:27], v11, v26
	v_cmp_lt_i32_e64 s[0:1], s0, v32
	v_cmp_lt_f32_e64 s[22:23], v11, v26
	s_and_b64 s[26:27], s[0:1], s[26:27]
	s_movk_i32 s30, 0xffeb
	s_or_b64 s[22:23], s[22:23], s[26:27]
	v_cmp_eq_f32_e64 s[26:27], v16, v26
	v_cmp_lt_i32_e64 s[30:31], s30, v32
	ds_bpermute_b32 v40, v17, v15 offset:192
	v_cndmask_b32_e64 v38, 0, 1, s[22:23]
	v_cmp_lt_f32_e64 s[22:23], v16, v26
	s_and_b64 s[26:27], s[30:31], s[26:27]
	s_movk_i32 s36, 0xffe7
	s_or_b64 s[22:23], s[22:23], s[26:27]
	v_cmp_eq_f32_e64 s[26:27], v9, v26
	v_cmp_lt_i32_e64 s[36:37], s36, v32
	v_cndmask_b32_e64 v39, 0, 1, s[22:23]
	v_cmp_lt_f32_e64 s[22:23], v9, v26
	s_and_b64 s[26:27], s[36:37], s[26:27]
	s_or_b64 s[22:23], s[22:23], s[26:27]
	v_cndmask_b32_e64 v26, 0, 1, s[22:23]
	s_waitcnt lgkmcnt(0)
	v_cmp_eq_f32_e64 s[36:37], v14, v40
	v_cmp_lt_i32_e64 s[22:23], 7, v32
	v_cmp_lt_f32_e64 s[26:27], v14, v40
	s_and_b64 s[36:37], s[22:23], s[36:37]
	s_or_b64 s[26:27], s[26:27], s[36:37]
	v_addc_co_u32_e64 v19, s[26:27], v19, v27, s[26:27]
	v_cmp_eq_f32_e64 s[36:37], v15, v40
	v_cmp_lt_f32_e64 s[26:27], v15, v40
	s_and_b64 s[36:37], s[18:19], s[36:37]
	s_or_b64 s[26:27], s[26:27], s[36:37]
	v_addc_co_u32_e64 v20, s[26:27], v20, v28, s[26:27]
	v_cmp_eq_f32_e64 s[36:37], v12, v40
	v_cmp_lt_f32_e64 s[26:27], v12, v40
	s_and_b64 s[36:37], s[20:21], s[36:37]
	s_or_b64 s[26:27], s[26:27], s[36:37]
	v_addc_co_u32_e64 v21, s[26:27], v21, v29, s[26:27]
	v_cmp_eq_f32_e64 s[36:37], v13, v40
	v_cmp_lt_f32_e64 s[26:27], v13, v40
	s_and_b64 s[36:37], s[24:25], s[36:37]
	s_or_b64 s[26:27], s[26:27], s[36:37]
	v_addc_co_u32_e64 v22, s[26:27], v22, v30, s[26:27]
	v_cmp_eq_f32_e64 s[36:37], v10, v40
	v_cmp_lt_f32_e64 s[26:27], v10, v40
	s_and_b64 s[36:37], s[28:29], s[36:37]
	s_or_b64 s[26:27], s[26:27], s[36:37]
	v_addc_co_u32_e64 v23, s[26:27], v23, v31, s[26:27]
	v_cmp_eq_f32_e64 s[36:37], v11, v40
	v_cmp_lt_f32_e64 s[26:27], v11, v40
	s_and_b64 s[36:37], s[34:35], s[36:37]
	s_or_b64 s[26:27], s[26:27], s[36:37]
	v_addc_co_u32_e64 v24, s[26:27], v24, v38, s[26:27]
	v_cmp_eq_f32_e64 s[36:37], v16, v40
	v_cmp_lt_f32_e64 s[26:27], v16, v40
	s_and_b64 s[36:37], s[0:1], s[36:37]
	s_or_b64 s[26:27], s[26:27], s[36:37]
	v_addc_co_u32_e64 v25, s[26:27], v25, v39, s[26:27]
	v_cmp_eq_f32_e64 s[36:37], v9, v40
	v_cmp_lt_f32_e64 s[26:27], v9, v40
	s_and_b64 s[30:31], s[30:31], s[36:37]
	s_or_b64 s[26:27], s[26:27], s[30:31]
	v_addc_co_u32_e64 v18, s[26:27], v18, v26, s[26:27]
	ds_bpermute_b32 v26, v17, v12 offset:192
	v_cmp_lt_i32_e64 s[26:27], 11, v32
	ds_bpermute_b32 v40, v17, v13 offset:192
	s_waitcnt lgkmcnt(1)
	v_cmp_eq_f32_e64 s[36:37], v14, v26
	v_cmp_lt_f32_e64 s[30:31], v14, v26
	s_and_b64 s[36:37], s[26:27], s[36:37]
	s_or_b64 s[30:31], s[30:31], s[36:37]
	v_cmp_eq_f32_e64 s[36:37], v15, v26
	v_cndmask_b32_e64 v27, 0, 1, s[30:31]
	v_cmp_lt_f32_e64 s[30:31], v15, v26
	s_and_b64 s[36:37], s[22:23], s[36:37]
	s_or_b64 s[30:31], s[30:31], s[36:37]
	v_cmp_eq_f32_e64 s[36:37], v12, v26
	v_cndmask_b32_e64 v28, 0, 1, s[30:31]
	v_cmp_lt_f32_e64 s[30:31], v12, v26
	s_and_b64 s[36:37], s[18:19], s[36:37]
	s_or_b64 s[30:31], s[30:31], s[36:37]
	v_cmp_eq_f32_e64 s[36:37], v13, v26
	v_cndmask_b32_e64 v29, 0, 1, s[30:31]
	v_cmp_lt_f32_e64 s[30:31], v13, v26
	s_and_b64 s[36:37], s[20:21], s[36:37]
	s_or_b64 s[30:31], s[30:31], s[36:37]
	v_cmp_eq_f32_e64 s[36:37], v10, v26
	v_cndmask_b32_e64 v30, 0, 1, s[30:31]
	v_cmp_lt_f32_e64 s[30:31], v10, v26
	s_and_b64 s[36:37], s[24:25], s[36:37]
	s_or_b64 s[30:31], s[30:31], s[36:37]
	v_cmp_eq_f32_e64 s[36:37], v11, v26
	v_cndmask_b32_e64 v31, 0, 1, s[30:31]
	v_cmp_lt_f32_e64 s[30:31], v11, v26
	s_and_b64 s[36:37], s[28:29], s[36:37]
	s_or_b64 s[30:31], s[30:31], s[36:37]
	v_cmp_eq_f32_e64 s[36:37], v16, v26
	v_cndmask_b32_e64 v38, 0, 1, s[30:31]
	v_cmp_lt_f32_e64 s[30:31], v16, v26
	s_and_b64 s[36:37], s[34:35], s[36:37]
	s_or_b64 s[30:31], s[30:31], s[36:37]
	v_cmp_eq_f32_e64 s[36:37], v9, v26
	v_cndmask_b32_e64 v39, 0, 1, s[30:31]
	v_cmp_lt_f32_e64 s[30:31], v9, v26
	s_and_b64 s[0:1], s[0:1], s[36:37]
	s_or_b64 s[0:1], s[30:31], s[0:1]
	s_waitcnt lgkmcnt(0)
	v_cmp_eq_f32_e64 s[36:37], v14, v40
	v_cmp_lt_i32_e64 s[30:31], 15, v32
	v_cndmask_b32_e64 v26, 0, 1, s[0:1]
	v_cmp_lt_f32_e64 s[0:1], v14, v40
	s_and_b64 s[36:37], s[30:31], s[36:37]
	s_or_b64 s[0:1], s[0:1], s[36:37]
	v_addc_co_u32_e64 v19, s[0:1], v19, v27, s[0:1]
	v_cmp_eq_f32_e64 s[36:37], v15, v40
	v_cmp_lt_f32_e64 s[0:1], v15, v40
	s_and_b64 s[36:37], s[26:27], s[36:37]
	s_or_b64 s[0:1], s[0:1], s[36:37]
	v_addc_co_u32_e64 v20, s[0:1], v20, v28, s[0:1]
	v_cmp_eq_f32_e64 s[36:37], v12, v40
	v_cmp_lt_f32_e64 s[0:1], v12, v40
	s_and_b64 s[36:37], s[22:23], s[36:37]
	s_or_b64 s[0:1], s[0:1], s[36:37]
	v_addc_co_u32_e64 v21, s[0:1], v21, v29, s[0:1]
	v_cmp_eq_f32_e64 s[36:37], v13, v40
	v_cmp_lt_f32_e64 s[0:1], v13, v40
	s_and_b64 s[36:37], s[18:19], s[36:37]
	s_or_b64 s[0:1], s[0:1], s[36:37]
	v_addc_co_u32_e64 v22, s[0:1], v22, v30, s[0:1]
	v_cmp_eq_f32_e64 s[36:37], v10, v40
	v_cmp_lt_f32_e64 s[0:1], v10, v40
	s_and_b64 s[36:37], s[20:21], s[36:37]
	s_or_b64 s[0:1], s[0:1], s[36:37]
	v_addc_co_u32_e64 v23, s[0:1], v23, v31, s[0:1]
	v_cmp_eq_f32_e64 s[36:37], v11, v40
	v_cmp_lt_f32_e64 s[0:1], v11, v40
	s_and_b64 s[36:37], s[24:25], s[36:37]
	s_or_b64 s[0:1], s[0:1], s[36:37]
	v_addc_co_u32_e64 v24, s[0:1], v24, v38, s[0:1]
	v_cmp_eq_f32_e64 s[36:37], v16, v40
	v_cmp_lt_f32_e64 s[0:1], v16, v40
	s_and_b64 s[36:37], s[28:29], s[36:37]
	s_or_b64 s[0:1], s[0:1], s[36:37]
	v_addc_co_u32_e64 v25, s[0:1], v25, v39, s[0:1]
	v_cmp_eq_f32_e64 s[36:37], v9, v40
	v_cmp_lt_f32_e64 s[0:1], v9, v40
	s_and_b64 s[34:35], s[34:35], s[36:37]
	s_or_b64 s[0:1], s[0:1], s[34:35]
	v_addc_co_u32_e64 v18, s[0:1], v18, v26, s[0:1]
	ds_bpermute_b32 v26, v17, v10 offset:192
	v_cmp_lt_i32_e64 s[34:35], 19, v32
	ds_bpermute_b32 v40, v17, v11 offset:192
	s_waitcnt lgkmcnt(1)
	v_cmp_eq_f32_e64 s[36:37], v14, v26
	v_cmp_lt_f32_e64 s[0:1], v14, v26
	s_and_b64 s[36:37], s[34:35], s[36:37]
	s_or_b64 s[0:1], s[0:1], s[36:37]
	v_cmp_eq_f32_e64 s[36:37], v15, v26
	v_cndmask_b32_e64 v27, 0, 1, s[0:1]
	v_cmp_lt_f32_e64 s[0:1], v15, v26
	s_and_b64 s[36:37], s[30:31], s[36:37]
	s_or_b64 s[0:1], s[0:1], s[36:37]
	v_cmp_eq_f32_e64 s[36:37], v12, v26
	v_cndmask_b32_e64 v28, 0, 1, s[0:1]
	v_cmp_lt_f32_e64 s[0:1], v12, v26
	s_and_b64 s[36:37], s[26:27], s[36:37]
	s_or_b64 s[0:1], s[0:1], s[36:37]
	v_cmp_eq_f32_e64 s[36:37], v13, v26
	v_cndmask_b32_e64 v29, 0, 1, s[0:1]
	v_cmp_lt_f32_e64 s[0:1], v13, v26
	s_and_b64 s[36:37], s[22:23], s[36:37]
	s_or_b64 s[0:1], s[0:1], s[36:37]
	v_cmp_eq_f32_e64 s[36:37], v10, v26
	v_cndmask_b32_e64 v30, 0, 1, s[0:1]
	v_cmp_lt_f32_e64 s[0:1], v10, v26
	s_and_b64 s[36:37], s[18:19], s[36:37]
	s_or_b64 s[0:1], s[0:1], s[36:37]
	v_cmp_eq_f32_e64 s[36:37], v11, v26
	v_cndmask_b32_e64 v31, 0, 1, s[0:1]
	v_cmp_lt_f32_e64 s[0:1], v11, v26
	s_and_b64 s[36:37], s[20:21], s[36:37]
	s_or_b64 s[0:1], s[0:1], s[36:37]
	v_cmp_eq_f32_e64 s[36:37], v16, v26
	v_cndmask_b32_e64 v38, 0, 1, s[0:1]
	v_cmp_lt_f32_e64 s[0:1], v16, v26
	s_and_b64 s[36:37], s[24:25], s[36:37]
	s_or_b64 s[0:1], s[0:1], s[36:37]
	v_cmp_eq_f32_e64 s[36:37], v9, v26
	v_cndmask_b32_e64 v39, 0, 1, s[0:1]
	v_cmp_lt_f32_e64 s[0:1], v9, v26
	s_and_b64 s[28:29], s[28:29], s[36:37]
	s_or_b64 s[0:1], s[0:1], s[28:29]
	v_cndmask_b32_e64 v26, 0, 1, s[0:1]
	s_waitcnt lgkmcnt(0)
	v_cmp_eq_f32_e64 s[36:37], v14, v40
	v_cmp_lt_i32_e64 s[0:1], 23, v32
	v_cmp_lt_f32_e64 s[28:29], v14, v40
	s_and_b64 s[36:37], s[0:1], s[36:37]
	s_or_b64 s[28:29], s[28:29], s[36:37]
	v_addc_co_u32_e64 v19, s[28:29], v19, v27, s[28:29]
	v_cmp_eq_f32_e64 s[36:37], v15, v40
	v_cmp_lt_f32_e64 s[28:29], v15, v40
	s_and_b64 s[36:37], s[34:35], s[36:37]
	s_or_b64 s[28:29], s[28:29], s[36:37]
	v_addc_co_u32_e64 v20, s[28:29], v20, v28, s[28:29]
	v_cmp_eq_f32_e64 s[36:37], v12, v40
	v_cmp_lt_f32_e64 s[28:29], v12, v40
	s_and_b64 s[36:37], s[30:31], s[36:37]
	s_or_b64 s[28:29], s[28:29], s[36:37]
	v_addc_co_u32_e64 v21, s[28:29], v21, v29, s[28:29]
	v_cmp_eq_f32_e64 s[36:37], v13, v40
	v_cmp_lt_f32_e64 s[28:29], v13, v40
	s_and_b64 s[36:37], s[26:27], s[36:37]
	s_or_b64 s[28:29], s[28:29], s[36:37]
	v_addc_co_u32_e64 v22, s[28:29], v22, v30, s[28:29]
	v_cmp_eq_f32_e64 s[36:37], v10, v40
	v_cmp_lt_f32_e64 s[28:29], v10, v40
	s_and_b64 s[36:37], s[22:23], s[36:37]
	s_or_b64 s[28:29], s[28:29], s[36:37]
	v_addc_co_u32_e64 v23, s[28:29], v23, v31, s[28:29]
	v_cmp_eq_f32_e64 s[36:37], v11, v40
	v_cmp_lt_f32_e64 s[28:29], v11, v40
	s_and_b64 s[36:37], s[18:19], s[36:37]
	s_or_b64 s[28:29], s[28:29], s[36:37]
	v_addc_co_u32_e64 v24, s[28:29], v24, v38, s[28:29]
	v_cmp_eq_f32_e64 s[36:37], v16, v40
	v_cmp_lt_f32_e64 s[28:29], v16, v40
	s_and_b64 s[36:37], s[20:21], s[36:37]
	s_or_b64 s[28:29], s[28:29], s[36:37]
	v_addc_co_u32_e64 v25, s[28:29], v25, v39, s[28:29]
	v_cmp_eq_f32_e64 s[36:37], v9, v40
	v_cmp_lt_f32_e64 s[28:29], v9, v40
	s_and_b64 s[24:25], s[24:25], s[36:37]
	s_or_b64 s[24:25], s[28:29], s[24:25]
	v_addc_co_u32_e64 v18, s[24:25], v18, v26, s[24:25]
	ds_bpermute_b32 v26, v17, v16 offset:192
	v_cmp_lt_i32_e64 s[36:37], 27, v32
	ds_bpermute_b32 v17, v17, v9 offset:192
	s_waitcnt lgkmcnt(1)
	v_cmp_eq_f32_e64 s[28:29], v14, v26
	v_cmp_lt_f32_e64 s[24:25], v14, v26
	s_and_b64 s[28:29], s[36:37], s[28:29]
	s_or_b64 s[24:25], s[24:25], s[28:29]
	v_cmp_eq_f32_e64 s[28:29], v15, v26
	v_cndmask_b32_e64 v27, 0, 1, s[24:25]
	v_cmp_lt_f32_e64 s[24:25], v15, v26
	s_and_b64 s[28:29], s[0:1], s[28:29]
	s_or_b64 s[24:25], s[24:25], s[28:29]
	v_cmp_eq_f32_e64 s[28:29], v12, v26
	v_cndmask_b32_e64 v28, 0, 1, s[24:25]
	v_cmp_lt_f32_e64 s[24:25], v12, v26
	s_and_b64 s[28:29], s[34:35], s[28:29]
	s_or_b64 s[24:25], s[24:25], s[28:29]
	v_cmp_eq_f32_e64 s[28:29], v13, v26
	v_cndmask_b32_e64 v29, 0, 1, s[24:25]
	v_cmp_lt_f32_e64 s[24:25], v13, v26
	s_and_b64 s[28:29], s[30:31], s[28:29]
	s_or_b64 s[24:25], s[24:25], s[28:29]
	v_cmp_eq_f32_e64 s[28:29], v10, v26
	v_cndmask_b32_e64 v30, 0, 1, s[24:25]
	v_cmp_lt_f32_e64 s[24:25], v10, v26
	s_and_b64 s[28:29], s[26:27], s[28:29]
	s_or_b64 s[24:25], s[24:25], s[28:29]
	v_cmp_eq_f32_e64 s[28:29], v11, v26
	v_cndmask_b32_e64 v31, 0, 1, s[24:25]
	v_cmp_lt_f32_e64 s[24:25], v11, v26
	s_and_b64 s[28:29], s[22:23], s[28:29]
	s_or_b64 s[24:25], s[24:25], s[28:29]
	v_cmp_eq_f32_e64 s[28:29], v16, v26
	v_cndmask_b32_e64 v38, 0, 1, s[24:25]
	v_cmp_lt_f32_e64 s[24:25], v16, v26
	s_and_b64 s[28:29], s[18:19], s[28:29]
	s_or_b64 s[24:25], s[24:25], s[28:29]
	v_cmp_eq_f32_e64 s[28:29], v9, v26
	v_cndmask_b32_e64 v39, 0, 1, s[24:25]
	v_cmp_lt_f32_e64 s[24:25], v9, v26
	s_and_b64 s[20:21], s[20:21], s[28:29]
	s_or_b64 s[20:21], s[24:25], s[20:21]
	s_waitcnt lgkmcnt(0)
	v_cmp_eq_f32_e64 s[24:25], v14, v17
	v_cmp_lt_i32_e64 s[28:29], 31, v32
	v_cndmask_b32_e64 v26, 0, 1, s[20:21]
	v_cmp_lt_f32_e64 s[20:21], v14, v17
	s_and_b64 s[24:25], s[28:29], s[24:25]
	s_or_b64 s[20:21], s[20:21], s[24:25]
	v_addc_co_u32_e64 v14, s[20:21], v19, v27, s[20:21]
	v_cmp_eq_f32_e64 s[24:25], v15, v17
	v_cmp_lt_f32_e64 s[20:21], v15, v17
	s_and_b64 s[24:25], s[36:37], s[24:25]
	s_or_b64 s[20:21], s[20:21], s[24:25]
	v_addc_co_u32_e64 v15, s[20:21], v20, v28, s[20:21]
	v_cmp_eq_f32_e64 s[24:25], v12, v17
	v_cmp_lt_f32_e64 s[20:21], v12, v17
	s_and_b64 s[0:1], s[0:1], s[24:25]
	s_or_b64 s[0:1], s[20:21], s[0:1]
	v_addc_co_u32_e64 v12, s[0:1], v21, v29, s[0:1]
	v_cmp_eq_f32_e64 s[20:21], v13, v17
	v_cmp_lt_f32_e64 s[0:1], v13, v17
	s_and_b64 s[20:21], s[34:35], s[20:21]
	s_or_b64 s[0:1], s[0:1], s[20:21]
	v_addc_co_u32_e64 v13, s[0:1], v22, v30, s[0:1]
	v_cmp_eq_f32_e64 s[20:21], v10, v17
	v_cmp_lt_f32_e64 s[0:1], v10, v17
	s_and_b64 s[20:21], s[30:31], s[20:21]
	s_or_b64 s[0:1], s[0:1], s[20:21]
	v_addc_co_u32_e64 v10, s[0:1], v23, v31, s[0:1]
	v_cmp_eq_f32_e64 s[20:21], v11, v17
	v_cmp_lt_f32_e64 s[0:1], v11, v17
	s_and_b64 s[20:21], s[26:27], s[20:21]
	s_or_b64 s[0:1], s[0:1], s[20:21]
	v_addc_co_u32_e64 v11, s[0:1], v24, v38, s[0:1]
	v_cmp_eq_f32_e64 s[20:21], v16, v17
	v_cmp_lt_f32_e64 s[0:1], v16, v17
	s_and_b64 s[20:21], s[22:23], s[20:21]
	s_or_b64 s[0:1], s[0:1], s[20:21]
	v_addc_co_u32_e64 v16, s[0:1], v25, v39, s[0:1]
	v_cmp_eq_f32_e64 s[20:21], v9, v17
	v_cmp_lt_f32_e64 s[0:1], v9, v17
	s_and_b64 s[18:19], s[18:19], s[20:21]
	s_or_b64 s[0:1], s[0:1], s[18:19]
	v_addc_co_u32_e64 v9, s[0:1], v18, v26, s[0:1]
	v_cmp_lt_u32_e64 s[0:1], 7, v14
	s_or_b64 s[0:1], vcc, s[0:1]
	v_lshlrev_b32_e64 v14, v32, 1
	v_cmp_lt_u32_e32 vcc, 7, v15
	v_cndmask_b32_e64 v14, v14, 0, s[0:1]
	s_or_b64 s[0:1], s[4:5], vcc
	v_cmp_lt_u32_e32 vcc, 7, v12
	v_cndmask_b32_e64 v2, v2, 0, s[0:1]
	s_or_b64 s[0:1], s[6:7], vcc
	v_cmp_lt_u32_e32 vcc, 7, v13
	v_cndmask_b32_e64 v3, v3, 0, s[0:1]
	s_or_b64 s[0:1], s[8:9], vcc
	v_or_b32_e32 v2, v2, v14
	v_cndmask_b32_e64 v4, v4, 0, s[0:1]
	v_cmp_lt_u32_e32 vcc, 7, v10
	v_or3_b32 v2, v2, v3, v4
	s_or_b64 s[0:1], s[10:11], vcc
	v_lshlrev_b32_e64 v3, v5, 1
	v_cmp_lt_u32_e32 vcc, 7, v11
	v_cndmask_b32_e64 v3, v3, 0, s[0:1]
	s_or_b64 s[0:1], s[12:13], vcc
	v_lshlrev_b32_e64 v4, v6, 1
	v_cndmask_b32_e64 v4, v4, 0, s[0:1]
	v_cmp_lt_u32_e32 vcc, 7, v16
	v_or3_b32 v2, v2, v3, v4
	s_or_b64 s[0:1], s[14:15], vcc
	v_lshlrev_b32_e64 v3, v7, 1
	v_cmp_lt_u32_e32 vcc, 7, v9
	v_cndmask_b32_e64 v3, v3, 0, s[0:1]
	s_or_b64 s[0:1], s[16:17], vcc
	v_lshlrev_b32_e64 v4, v8, 1
	v_cndmask_b32_e64 v4, v4, 0, s[0:1]
	v_or3_b32 v2, v2, v3, v4
	ds_bpermute_b32 v3, v193, v2
	v_cmp_lt_i32_e32 vcc, v214, v213
	s_waitcnt lgkmcnt(0)
	v_or_b32_e32 v2, v2, v3
	ds_bpermute_b32 v3, v194, v2
	s_waitcnt lgkmcnt(0)
	v_or_b32_e32 v195, v2, v3
	v_cndmask_b32_e32 v2, v211, v214, vcc
	v_lshlrev_b32_e32 v2, 2, v2
	ds_bpermute_b32 v2, v2, v195
	v_cmp_lt_i32_e32 vcc, v215, v213
	s_waitcnt lgkmcnt(0)
	v_or_b32_e32 v2, v195, v2
	v_cndmask_b32_e32 v3, v211, v215, vcc
	v_lshlrev_b32_e32 v3, 2, v3
	ds_bpermute_b32 v3, v3, v2
	v_cmp_lt_i32_e32 vcc, v216, v213
	s_waitcnt lgkmcnt(0)
	v_or_b32_e32 v2, v2, v3
	v_cndmask_b32_e32 v3, v211, v216, vcc
	v_lshlrev_b32_e32 v3, 2, v3
	ds_bpermute_b32 v3, v3, v2
	v_cmp_lt_i32_e32 vcc, v217, v213
	s_waitcnt lgkmcnt(0)
	v_or_b32_e32 v2, v2, v3
	v_cndmask_b32_e32 v3, v211, v217, vcc
	v_lshlrev_b32_e32 v3, 2, v3
	ds_bpermute_b32 v3, v3, v2
	s_waitcnt lgkmcnt(0)
	v_or_b32_e32 v40, v2, v3
	s_add_u32 s16, s86, 0x29200000
	v_lshl_add_u64 v[0:1], v[146:147], 1, v[0:1]
	s_mov_b64 s[0:1], 0x15200000
	s_addc_u32 s17, s87, 0
	v_lshl_add_u64 v[38:39], v[0:1], 0, s[0:1]
	s_lshl_b32 s82, s2, 9
	v_lshl_add_u64 v[28:29], v[38:39], 0, s[82:83]
	global_load_dwordx4 v[0:3], v[28:29], off
	global_load_dwordx4 v[4:7], v[28:29], off offset:64
	global_load_dwordx4 v[8:11], v[28:29], off offset:128
	global_load_dwordx4 v[12:15], v[28:29], off offset:192
	global_load_dwordx4 v[16:19], v[28:29], off offset:256
	global_load_dwordx4 v[20:23], v[28:29], off offset:320
	global_load_dwordx4 v[24:27], v[28:29], off offset:384
	s_nop 0
	global_load_dwordx4 v[28:31], v[28:29], off offset:448
	v_lshlrev_b64 v[32:33], 3, v[32:33]
	v_sub_co_u32_e32 v32, vcc, 0, v32
	v_mul_f32_e32 v196, 0x3fb8aa3b, v34
	v_readfirstlane_b32 s18, v40
	v_subb_co_u32_e32 v33, vcc, 0, v33, vcc
	v_mov_b32_e32 v34, 0x1ff
	s_ff1_i32_b32 s0, s18
	v_sub_co_u32_e32 v34, vcc, s81, v34
	s_ashr_i32 s95, s94, 31
	s_lshl_b32 s19, s0, 6
	v_readfirstlane_b32 s0, v34
	s_lshl_b64 s[6:7], s[94:95], 19
	s_lshl_b32 s4, s2, 6
	s_lshl_b64 s[8:9], s[84:85], 18
	s_sub_i32 s2, s81, 17
	s_add_i32 s20, s18, -1
	s_and_b32 s5, s0, 0xffffffe0
	v_lshl_add_u64 v[32:33], v[38:39], 0, v[32:33]
	s_and_b64 s[0:1], vcc, exec
	v_lshlrev_b32_e32 v34, 11, v190
	v_mul_f32_e32 v197, 0x3fb8aa3b, v35
	v_mul_f32_e32 v198, 0x3fb8aa3b, v36
	v_mul_f32_e32 v199, 0x3fb8aa3b, v37
	s_cselect_b32 s21, 0, s5
	v_add_u32_e32 v200, 0xfffffe01, v191
	v_lshl_add_u64 v[150:151], v[32:33], 0, s[82:83]
	s_mov_b64 s[10:11], 0
	s_lshl_b32 s22, s4, 1
	v_lshlrev_b32_e32 v152, 1, v34
	v_readlane_b32 s56, v252, 21
	v_readlane_b32 s57, v252, 22
	v_lshlrev_b32_e32 v250, 1, v144
	v_lshrrev_b32_e32 v255, 2, v190
	v_and_b32_e32 v251, 3, v190
	v_lshl_or_b32 v255, v255, 3, v251
	v_mov_b32_e32 v251, 0
	s_branch .LBB0_191

.LBB0_191:
	s_xor_b64 s[12:13], s[10:11], -1
	s_and_b64 s[0:1], s[10:11], exec
	s_cselect_b32 s82, s21, s19
	s_cmp_lt_i32 s82, 0
	s_cbranch_scc1 .LBB0_202
	s_lshl_b32 s0, s38, 25
	s_add_u32 s4, s16, s0
	s_addc_u32 s5, s17, 0
	s_add_u32 s0, s4, s6
	s_addc_u32 s1, s5, s7
	s_add_u32 s0, s0, s22
	v_or_b32_e32 v32, s82, v255
	s_addc_u32 s1, s1, 0
	v_or_b32_e32 v160, 4, v32
	v_mov_b32_e32 v33, v161
	v_lshl_add_u64 v[158:159], v[146:147], 1, s[0:1]
	v_lshlrev_b64 v[34:35], 8, v[160:161]
	v_lshlrev_b64 v[32:33], 8, v[32:33]
	v_lshl_add_u64 v[34:35], v[158:159], 0, v[34:35]
	v_lshl_add_u64 v[32:33], v[158:159], 0, v[32:33]
	global_load_dwordx4 v[96:99], v[34:35], off offset:64
	global_load_dwordx4 v[100:103], v[34:35], off
	global_load_dwordx4 v[104:107], v[32:33], off offset:64
	global_load_dwordx4 v[108:111], v[32:33], off
	s_add_u32 s0, s4, s8
	s_addc_u32 s1, s5, s9
	v_lshl_add_u64 v[32:33], v[250:251], 1, s[0:1]
	v_mov_b32_e32 v153, v161
	s_and_b64 s[4:5], s[10:11], exec
	v_lshl_add_u64 v[32:33], v[32:33], 0, v[152:153]
	s_mov_b64 s[0:1], 0x1000000
	s_cselect_b32 s4, -1, s20
	v_cndmask_b32_e64 v160, 0, v200, s[10:11]
	v_lshl_add_u64 v[170:171], v[32:33], 0, s[0:1]
	v_mov_b32_e32 v32, 0
	s_and_b32 s4, s4, s18
	v_add_u32_e32 v153, -1, v160
	v_mov_b32_e32 v172, 0xf149f2ca
	v_mov_b32_e32 v177, 0xf149f2ca
	v_mov_b32_e32 v175, 0xf149f2ca
	v_mov_b32_e32 v173, 0xf149f2ca
	v_mov_b32_e32 v33, v32
	v_mov_b32_e32 v34, v32
	v_mov_b32_e32 v35, v32
	v_mov_b32_e32 v36, v32
	v_mov_b32_e32 v37, v32
	v_mov_b32_e32 v38, v32
	v_mov_b32_e32 v39, v32
	v_mov_b32_e32 v40, v32
	v_mov_b32_e32 v41, v32
	v_mov_b32_e32 v42, v32
	v_mov_b32_e32 v43, v32
	v_mov_b32_e32 v44, v32
	v_mov_b32_e32 v45, v32
	v_mov_b32_e32 v46, v32
	v_mov_b32_e32 v47, v32
	v_mov_b32_e32 v48, v32
	v_mov_b32_e32 v49, v32
	v_mov_b32_e32 v50, v32
	v_mov_b32_e32 v51, v32
	v_mov_b32_e32 v52, v32
	v_mov_b32_e32 v53, v32
	v_mov_b32_e32 v54, v32
	v_mov_b32_e32 v55, v32
	v_mov_b32_e32 v56, v32
	v_mov_b32_e32 v57, v32
	v_mov_b32_e32 v58, v32
	v_mov_b32_e32 v59, v32
	v_mov_b32_e32 v60, v32
	v_mov_b32_e32 v61, v32
	v_mov_b32_e32 v62, v32
	v_mov_b32_e32 v63, v32
	v_mov_b32_e32 v64, v32
	v_mov_b32_e32 v65, v32
	v_mov_b32_e32 v66, v32
	v_mov_b32_e32 v67, v32
	v_mov_b32_e32 v68, v32
	v_mov_b32_e32 v69, v32
	v_mov_b32_e32 v70, v32
	v_mov_b32_e32 v71, v32
	v_mov_b32_e32 v72, v32
	v_mov_b32_e32 v73, v32
	v_mov_b32_e32 v74, v32
	v_mov_b32_e32 v75, v32
	v_mov_b32_e32 v76, v32
	v_mov_b32_e32 v77, v32
	v_mov_b32_e32 v78, v32
	v_mov_b32_e32 v79, v32
	v_mov_b32_e32 v80, v32
	v_mov_b32_e32 v81, v32
	v_mov_b32_e32 v82, v32
	v_mov_b32_e32 v83, v32
	v_mov_b32_e32 v84, v32
	v_mov_b32_e32 v85, v32
	v_mov_b32_e32 v86, v32
	v_mov_b32_e32 v87, v32
	v_mov_b32_e32 v88, v32
	v_mov_b32_e32 v89, v32
	v_mov_b32_e32 v90, v32
	v_mov_b32_e32 v91, v32
	v_mov_b32_e32 v92, v32
	v_mov_b32_e32 v93, v32
	v_mov_b32_e32 v94, v32
	v_mov_b32_e32 v95, v32
	v_mov_b32_e32 v156, v32
	v_mov_b32_e32 v157, v32
	v_mov_b32_e32 v154, v32
	v_mov_b32_e32 v155, v32
	s_andn2_b64 vcc, exec, s[12:13]
	s_mov_b64 s[0:1], -1
	s_cbranch_vccnz .LBB0_198

.LBB0_200:
	s_lshr_b32 s0, s82, 6
	s_lshl_b32 s0, 1, s0
	v_and_b32_e32 v112, s0, v195
	v_cmp_ne_u32_e32 vcc, 0, v112
	s_or_b64 s[14:15], s[10:11], vcc
	s_cmp_lt_i32 s23, 0
	s_cselect_b64 s[4:5], -1, 0
	s_and_b64 s[0:1], s[4:5], exec
	s_cselect_b32 s0, s82, s23
	v_add_u32_e32 v120, s0, v255
	v_ashrrev_i32_e32 v121, 31, v120
	v_lshlrev_b64 v[112:113], 8, v[120:121]
	v_add_u32_e32 v120, 4, v120
	v_ashrrev_i32_e32 v121, 31, v120
	v_lshl_add_u64 v[128:129], s[82:83], 1, v[170:171]
	v_lshlrev_b64 v[120:121], 8, v[120:121]
	v_add_co_u32_e32 v130, vcc, s3, v128
	v_lshl_add_u64 v[116:117], v[158:159], 0, v[112:113]
	v_lshl_add_u64 v[124:125], v[158:159], 0, v[120:121]
	v_addc_co_u32_e32 v131, vcc, 0, v129, vcc
	s_mov_b32 s0, 0x20000
	global_load_dwordx4 v[136:139], v[128:129], off
	s_nop 0
	global_load_dwordx4 v[140:143], v[130:131], off
	s_nop 0
	v_add_co_u32_e32 v130, vcc, s0, v128
	s_mov_b32 s0, 0x30000
	s_nop 0
	v_addc_co_u32_e32 v131, vcc, 0, v129, vcc
	global_load_dwordx4 v[132:135], v[130:131], off
	s_nop 0
	v_add_co_u32_e32 v130, vcc, s0, v128
	v_add_u32_e32 v166, s82, v250
	s_nop 0
	v_addc_co_u32_e32 v131, vcc, 0, v129, vcc
	global_load_dwordx4 v[128:131], v[130:131], off
	s_nop 0
	s_nop 0
	global_load_dwordx4 v[112:115], v[116:117], off
	s_nop 0
	global_load_dwordx4 v[116:119], v[116:117], off offset:64
	s_nop 0
	global_load_dwordx4 v[120:123], v[124:125], off
	s_nop 0
	global_load_dwordx4 v[124:127], v[124:125], off offset:64
	v_cmp_ge_i32_e32 vcc, v166, v160
	v_cmp_lt_i32_e64 s[0:1], v191, v166
	v_add_u32_e32 v167, 4, v166
	s_and_b64 vcc, s[14:15], vcc
	v_cndmask_b32_e64 v168, 0, v223, s[0:1]
	v_cndmask_b32_e32 v179, v223, v168, vcc
	v_cmp_ge_i32_e32 vcc, v167, v160
	v_cmp_gt_i32_e64 s[0:1], v167, v191
	s_and_b64 vcc, s[14:15], vcc
	v_add_u32_e32 v168, 6, v166
	v_cndmask_b32_e64 v167, 0, v223, s[0:1]
	v_cndmask_b32_e32 v181, v223, v167, vcc
	v_cmp_ge_i32_e32 vcc, v166, v153
	v_cmp_gt_i32_e64 s[0:1], v191, v166
	s_and_b64 s[0:1], s[0:1], vcc
	v_add_u32_e32 v167, 5, v166
	s_and_b64 s[0:1], s[14:15], s[0:1]
	v_cndmask_b32_e64 v183, v223, 0, s[0:1]
	v_cmp_ge_i32_e32 vcc, v167, v160
	v_cmp_gt_i32_e64 s[0:1], v167, v191
	s_and_b64 vcc, s[14:15], vcc
	s_waitcnt vmcnt(8)
	v_mfma_f32_16x16x32_bf16 v[228:231], v[108:111], v[0:3], 0
	v_cndmask_b32_e64 v167, 0, v223, s[0:1]
	v_cndmask_b32_e32 v185, v223, v167, vcc
	v_add_u32_e32 v167, 2, v166
	v_cmp_ge_i32_e32 vcc, v167, v160
	v_cmp_gt_i32_e64 s[0:1], v167, v191
	s_and_b64 vcc, s[14:15], vcc
	v_mfma_f32_16x16x32_bf16 v[232:235], v[100:103], v[0:3], 0
	v_cndmask_b32_e64 v167, 0, v223, s[0:1]
	v_cndmask_b32_e32 v187, v223, v167, vcc
	v_cmp_ge_i32_e32 vcc, v168, v160
	v_cmp_gt_i32_e64 s[0:1], v168, v191
	s_and_b64 vcc, s[14:15], vcc
	v_add_u32_e32 v168, 7, v166
	v_cndmask_b32_e64 v167, 0, v223, s[0:1]
	v_cndmask_b32_e32 v189, v223, v167, vcc
	v_add_u32_e32 v167, 3, v166
	v_sub_u32_e32 v166, v191, v166
	v_cvt_f32_i32_e32 v204, v166
	v_cmp_ge_i32_e32 vcc, v167, v160
	v_cmp_gt_i32_e64 s[0:1], v167, v191
	s_and_b64 vcc, s[14:15], vcc
	v_mfma_f32_16x16x32_bf16 v[228:231], v[104:107], v[4:7], v[228:231]
	v_cndmask_b32_e64 v167, 0, v223, s[0:1]
	v_cndmask_b32_e32 v202, v223, v167, vcc
	v_cmp_ge_i32_e32 vcc, v168, v160
	v_mfma_f32_16x16x32_bf16 v[232:235], v[96:99], v[4:7], v[232:235]
	v_cmp_gt_i32_e64 s[0:1], v168, v191
	s_and_b64 vcc, s[14:15], vcc
	v_mul_f32_e64 v166, -v196, v204
	v_cndmask_b32_e64 v167, 0, v223, s[0:1]
	v_cndmask_b32_e32 v203, v223, v167, vcc
	v_fma_f32 v167, 0, v196, v166
	v_fmamk_f32 v168, v196, 0x40800000, v166
	v_fma_f32 v174, -v196, v204, v196
	v_fmamk_f32 v176, v196, 0x40a00000, v166
	v_fmac_f32_e32 v167, 0x3e38aa3b, v228
	v_fmac_f32_e32 v168, 0x3e38aa3b, v232
	v_fmac_f32_e32 v174, 0x3e38aa3b, v229
	v_fmac_f32_e32 v176, 0x3e38aa3b, v233
	v_add_f32_e32 v167, v179, v167
	v_add_f32_e32 v168, v181, v168
	v_add_f32_e32 v174, v183, v174
	v_add_f32_e32 v182, v185, v176
	v_max_f32_e32 v169, v167, v168
	v_max_f32_e32 v176, v174, v182
	v_max3_f32 v169, v169, s73, v176
	v_fma_f32 v176, 2.0, v196, v166
	v_fmamk_f32 v178, v196, 0x40c00000, v166
	v_fmamk_f32 v180, v196, 0x40400000, v166
	v_fmac_f32_e32 v166, 0x40e00000, v196
	v_fmac_f32_e32 v176, 0x3e38aa3b, v230
	v_fmac_f32_e32 v178, 0x3e38aa3b, v234
	v_fmac_f32_e32 v180, 0x3e38aa3b, v231
	v_fmac_f32_e32 v166, 0x3e38aa3b, v235
	v_add_f32_e32 v176, v187, v176
	v_add_f32_e32 v186, v189, v178
	v_add_f32_e32 v180, v202, v180
	v_add_f32_e32 v166, v203, v166
	v_max_f32_e32 v178, v176, v186
	v_max_f32_e32 v184, v180, v166
	v_max3_f32 v169, v169, v178, v184
	v_mov_b32_e32 v178, v169
	v_mfma_f32_16x16x32_bf16 v[232:235], v[100:103], v[8:11], 0
	v_fma_f32 v205, -v197, v204, v197
	v_permlane16_swap_b32_e32 v178, v169
	v_max_f32_e32 v169, v169, v178
	v_mov_b32_e32 v178, v169
	v_mfma_f32_16x16x32_bf16 v[232:235], v[96:99], v[12:15], v[232:235]
	s_nop 0
	v_permlane32_swap_b32_e32 v178, v169
	v_max3_f32 v201, v172, v169, v178
	v_sub_f32_e32 v167, v167, v201
	v_sub_f32_e32 v169, v172, v201
	v_exp_f32_e32 v172, v167
	v_sub_f32_e32 v167, v174, v201
	v_exp_f32_e32 v174, v167
	v_sub_f32_e32 v167, v176, v201
	v_exp_f32_e32 v176, v167
	v_sub_f32_e32 v167, v180, v201
	v_exp_f32_e32 v178, v167
	v_sub_f32_e32 v167, v168, v201
	v_exp_f32_e32 v180, v167
	v_sub_f32_e32 v167, v182, v201
	v_exp_f32_e32 v184, v167
	v_sub_f32_e32 v167, v186, v201
	v_sub_f32_e32 v166, v166, v201
	v_exp_f32_e32 v186, v167
	v_exp_f32_e32 v188, v166
	v_exp_f32_e32 v182, v169
	v_cvt_pk_bf16_f32 v228, v172, v174
	v_cvt_pk_bf16_f32 v229, v176, v178
	v_cvt_pk_bf16_f32 v230, v180, v184
	v_cvt_pk_bf16_f32 v231, v186, v188
	v_pk_mul_f32 v[94:95], v[94:95], v[182:183] op_sel_hi:[1,0]
	v_pk_mul_f32 v[92:93], v[92:93], v[182:183] op_sel_hi:[1,0]
	v_pk_mul_f32 v[90:91], v[90:91], v[182:183] op_sel_hi:[1,0]
	v_pk_mul_f32 v[88:89], v[88:89], v[182:183] op_sel_hi:[1,0]
	v_pk_mul_f32 v[86:87], v[86:87], v[182:183] op_sel_hi:[1,0]
	v_pk_mul_f32 v[84:85], v[84:85], v[182:183] op_sel_hi:[1,0]
	v_pk_mul_f32 v[82:83], v[82:83], v[182:183] op_sel_hi:[1,0]
	v_pk_mul_f32 v[80:81], v[80:81], v[182:183] op_sel_hi:[1,0]
	s_waitcnt vmcnt(4)
	v_mfma_f32_16x16x32_bf16 v[92:95], v[136:139], v[228:231], v[92:95]
	v_mul_f32_e64 v166, -v197, v204
	v_fma_f32 v167, 0, v197, v166
	v_fmamk_f32 v168, v197, 0x40800000, v166
	v_mfma_f32_16x16x32_bf16 v[88:91], v[140:143], v[228:231], v[88:91]
	v_fmac_f32_e32 v168, 0x3e38aa3b, v232
	v_add_f32_e32 v169, v181, v168
	v_mfma_f32_16x16x32_bf16 v[84:87], v[132:135], v[228:231], v[84:87]
	v_mfma_f32_16x16x32_bf16 v[80:83], v[128:131], v[228:231], v[80:83]
	v_mfma_f32_16x16x32_bf16 v[228:231], v[108:111], v[8:11], 0
	v_mfma_f32_16x16x32_bf16 v[228:231], v[104:107], v[12:15], v[228:231]
	s_nop 7
	v_fmac_f32_e32 v205, 0x3e38aa3b, v229
	v_add_f32_e32 v206, v183, v205
	v_fmamk_f32 v205, v197, 0x40a00000, v166
	v_fmac_f32_e32 v167, 0x3e38aa3b, v228
	v_fmac_f32_e32 v205, 0x3e38aa3b, v233
	v_add_f32_e32 v167, v179, v167
	v_add_f32_e32 v207, v185, v205
	v_max_f32_e32 v168, v167, v169
	v_max_f32_e32 v205, v206, v207
	v_max3_f32 v168, v168, s73, v205
	v_fma_f32 v205, 2.0, v197, v166
	v_fmac_f32_e32 v205, 0x3e38aa3b, v230
	v_add_f32_e32 v228, v187, v205
	v_fmamk_f32 v205, v197, 0x40c00000, v166
	v_fmamk_f32 v230, v197, 0x40400000, v166
	v_fmac_f32_e32 v166, 0x40e00000, v197
	v_fmac_f32_e32 v205, 0x3e38aa3b, v234
	v_fmac_f32_e32 v230, 0x3e38aa3b, v231
	v_fmac_f32_e32 v166, 0x3e38aa3b, v235
	v_add_f32_e32 v229, v189, v205
	v_add_f32_e32 v230, v202, v230
	v_add_f32_e32 v231, v203, v166
	v_max_f32_e32 v205, v228, v229
	v_max_f32_e32 v166, v230, v231
	v_max3_f32 v166, v168, v205, v166
	v_mov_b32_e32 v168, v166
	s_nop 1
	v_permlane16_swap_b32_e32 v168, v166
	v_max_f32_e32 v166, v166, v168
	v_mov_b32_e32 v168, v166
	s_nop 1
	v_permlane32_swap_b32_e32 v168, v166
	v_max3_f32 v205, v177, v166, v168
	v_sub_f32_e32 v166, v167, v205
	v_sub_f32_e32 v167, v206, v205
	v_exp_f32_e32 v168, v167
	v_sub_f32_e32 v167, v228, v205
	v_exp_f32_e32 v236, v167
	v_sub_f32_e32 v167, v230, v205
	v_exp_f32_e32 v238, v167
	v_sub_f32_e32 v167, v169, v205
	v_exp_f32_e32 v240, v167
	v_sub_f32_e32 v167, v207, v205
	v_exp_f32_e32 v242, v167
	v_sub_f32_e32 v167, v229, v205
	v_sub_f32_e32 v177, v177, v205
	v_exp_f32_e32 v244, v167
	v_sub_f32_e32 v167, v231, v205
	v_exp_f32_e32 v166, v166
	v_exp_f32_e32 v246, v167
	v_exp_f32_e32 v248, v177
	v_cvt_pk_bf16_f32 v229, v236, v238
	v_cvt_pk_bf16_f32 v228, v166, v168
	v_cvt_pk_bf16_f32 v230, v240, v242
	v_cvt_pk_bf16_f32 v231, v244, v246
	v_pk_mul_f32 v[78:79], v[78:79], v[248:249] op_sel_hi:[1,0]
	v_pk_mul_f32 v[76:77], v[76:77], v[248:249] op_sel_hi:[1,0]
	v_pk_mul_f32 v[74:75], v[74:75], v[248:249] op_sel_hi:[1,0]
	v_pk_mul_f32 v[72:73], v[72:73], v[248:249] op_sel_hi:[1,0]
	v_pk_mul_f32 v[70:71], v[70:71], v[248:249] op_sel_hi:[1,0]
	v_pk_mul_f32 v[68:69], v[68:69], v[248:249] op_sel_hi:[1,0]
	v_pk_mul_f32 v[66:67], v[66:67], v[248:249] op_sel_hi:[1,0]
	v_pk_mul_f32 v[64:65], v[64:65], v[248:249] op_sel_hi:[1,0]
	v_mfma_f32_16x16x32_bf16 v[76:79], v[136:139], v[228:231], v[76:79]
	v_mfma_f32_16x16x32_bf16 v[72:75], v[140:143], v[228:231], v[72:75]
	v_mfma_f32_16x16x32_bf16 v[68:71], v[132:135], v[228:231], v[68:71]
	v_mfma_f32_16x16x32_bf16 v[64:67], v[128:131], v[228:231], v[64:67]
	v_mfma_f32_16x16x32_bf16 v[228:231], v[108:111], v[16:19], 0
	v_mul_f32_e64 v167, -v198, v204
	v_fma_f32 v169, 0, v198, v167
	v_fmamk_f32 v177, v198, 0x40800000, v167
	v_mfma_f32_16x16x32_bf16 v[232:235], v[100:103], v[16:19], 0
	v_fma_f32 v207, -v198, v204, v198
	v_mfma_f32_16x16x32_bf16 v[108:111], v[108:111], v[24:27], 0
	v_mfma_f32_16x16x32_bf16 v[100:103], v[100:103], v[24:27], 0
	v_mfma_f32_16x16x32_bf16 v[228:231], v[104:107], v[20:23], v[228:231]
	v_mfma_f32_16x16x32_bf16 v[232:235], v[96:99], v[20:23], v[232:235]
	v_mfma_f32_16x16x32_bf16 v[104:107], v[104:107], v[28:31], v[108:111]
	s_nop 5
	v_fmac_f32_e32 v169, 0x3e38aa3b, v228
	v_fmamk_f32 v228, v198, 0x40a00000, v167
	v_fmac_f32_e32 v177, 0x3e38aa3b, v232
	v_mfma_f32_16x16x32_bf16 v[96:99], v[96:99], v[28:31], v[100:103]
	v_fmac_f32_e32 v207, 0x3e38aa3b, v229
	v_fmac_f32_e32 v228, 0x3e38aa3b, v233
	v_add_f32_e32 v169, v179, v169
	v_mul_f32_e64 v100, -v199, v204
	v_fma_f32 v101, 0, v199, v100
	v_fmac_f32_e32 v101, 0x3e38aa3b, v104
	v_fmamk_f32 v102, v199, 0x40800000, v100
	v_fma_f32 v103, -v199, v204, v199
	v_fmamk_f32 v104, v199, 0x40a00000, v100
	v_add_f32_e32 v177, v181, v177
	v_add_f32_e32 v207, v183, v207
	v_add_f32_e32 v228, v185, v228
	v_fmac_f32_e32 v102, 0x3e38aa3b, v96
	v_fmac_f32_e32 v103, 0x3e38aa3b, v105
	v_fmac_f32_e32 v104, 0x3e38aa3b, v97
	v_max_f32_e32 v206, v169, v177
	v_max_f32_e32 v229, v207, v228
	v_add_f32_e32 v101, v179, v101
	v_add_f32_e32 v96, v181, v102
	v_add_f32_e32 v103, v183, v103
	v_add_f32_e32 v97, v185, v104
	v_max3_f32 v206, v206, s73, v229
	v_fma_f32 v229, 2.0, v198, v167
	v_max_f32_e32 v102, v101, v96
	v_max_f32_e32 v104, v103, v97
	v_fmac_f32_e32 v229, 0x3e38aa3b, v230
	v_fmamk_f32 v230, v198, 0x40c00000, v167
	v_fmamk_f32 v233, v198, 0x40400000, v167
	v_fmac_f32_e32 v167, 0x40e00000, v198
	v_max3_f32 v102, v102, s73, v104
	v_fma_f32 v104, 2.0, v199, v100
	v_fmac_f32_e32 v230, 0x3e38aa3b, v234
	v_fmac_f32_e32 v233, 0x3e38aa3b, v231
	v_fmac_f32_e32 v167, 0x3e38aa3b, v235
	v_fmac_f32_e32 v104, 0x3e38aa3b, v106
	v_fmamk_f32 v105, v199, 0x40c00000, v100
	v_fmamk_f32 v106, v199, 0x40400000, v100
	v_fmac_f32_e32 v100, 0x40e00000, v199
	v_add_f32_e32 v229, v187, v229
	v_add_f32_e32 v230, v189, v230
	v_add_f32_e32 v231, v202, v233
	v_add_f32_e32 v233, v203, v167
	v_fmac_f32_e32 v105, 0x3e38aa3b, v98
	v_fmac_f32_e32 v106, 0x3e38aa3b, v107
	v_fmac_f32_e32 v100, 0x3e38aa3b, v99
	v_max_f32_e32 v232, v229, v230
	v_max_f32_e32 v167, v231, v233
	v_add_f32_e32 v104, v187, v104
	v_add_f32_e32 v98, v189, v105
	v_add_f32_e32 v106, v202, v106
	v_add_f32_e32 v99, v203, v100
	v_max3_f32 v167, v206, v232, v167
	v_max_f32_e32 v105, v104, v98
	v_max_f32_e32 v100, v106, v99
	v_mov_b32_e32 v206, v167
	v_max3_f32 v100, v102, v105, v100
	v_mov_b32_e32 v102, v100
	s_nop 0
	v_permlane16_swap_b32_e32 v206, v167
	s_nop 0
	v_permlane16_swap_b32_e32 v102, v100
	v_max_f32_e32 v167, v167, v206
	v_max_f32_e32 v100, v100, v102
	v_mov_b32_e32 v206, v167
	v_mov_b32_e32 v102, v100
	s_nop 1
	v_permlane32_swap_b32_e32 v206, v167
	v_permlane32_swap_b32_e32 v102, v100
	v_max3_f32 v206, v175, v167, v206
	v_sub_f32_e32 v177, v177, v206
	v_max3_f32 v202, v173, v100, v102
	v_sub_f32_e32 v167, v169, v206
	v_exp_f32_e32 v241, v177
	v_sub_f32_e32 v177, v228, v206
	v_sub_f32_e32 v101, v101, v202
	v_sub_f32_e32 v175, v175, v206
	v_exp_f32_e32 v167, v167
	v_sub_f32_e32 v169, v207, v206
	v_exp_f32_e32 v243, v177
	v_sub_f32_e32 v177, v230, v206
	v_sub_f32_e32 v100, v173, v202
	v_exp_f32_e32 v173, v101
	v_sub_f32_e32 v101, v103, v202
	v_sub_f32_e32 v96, v96, v202
	v_exp_f32_e32 v169, v169
	v_sub_f32_e32 v207, v229, v206
	v_exp_f32_e32 v245, v177
	v_sub_f32_e32 v177, v233, v206
	v_exp_f32_e32 v249, v175
	v_exp_f32_e32 v175, v101
	v_sub_f32_e32 v101, v104, v202
	v_exp_f32_e32 v181, v96
	v_sub_f32_e32 v96, v97, v202
	v_exp_f32_e32 v237, v207
	v_sub_f32_e32 v207, v231, v206
	v_exp_f32_e32 v247, v177
	v_exp_f32_e32 v177, v101
	v_sub_f32_e32 v101, v106, v202
	v_exp_f32_e32 v185, v96
	v_sub_f32_e32 v96, v98, v202
	v_exp_f32_e32 v239, v207
	v_exp_f32_e32 v179, v101
	v_exp_f32_e32 v187, v96
	v_sub_f32_e32 v96, v99, v202
	v_pk_add_f32 v[228:229], v[166:167], 0 op_sel_hi:[1,0]
	v_exp_f32_e32 v189, v96
	v_pk_add_f32 v[96:97], v[172:173], 0 op_sel_hi:[1,0]
	v_pk_add_f32 v[228:229], v[168:169], v[228:229]
	v_pk_add_f32 v[96:97], v[174:175], v[96:97]
	v_pk_add_f32 v[228:229], v[236:237], v[228:229]
	v_pk_add_f32 v[96:97], v[176:177], v[96:97]
	v_pk_add_f32 v[228:229], v[238:239], v[228:229]
	v_exp_f32_e32 v183, v100
	v_pk_add_f32 v[96:97], v[178:179], v[96:97]
	v_pk_add_f32 v[228:229], v[240:241], v[228:229]
	v_pk_add_f32 v[96:97], v[180:181], v[96:97]
	v_pk_add_f32 v[228:229], v[242:243], v[228:229]
	v_pk_add_f32 v[96:97], v[184:185], v[96:97]
	v_pk_add_f32 v[228:229], v[244:245], v[228:229]
	v_pk_add_f32 v[96:97], v[186:187], v[96:97]
	v_pk_add_f32 v[228:229], v[246:247], v[228:229]
	v_mov_b32_e32 v166, v249
	v_pk_add_f32 v[96:97], v[188:189], v[96:97]
	v_mov_b32_e32 v100, v183
	v_pk_fma_f32 v[156:157], v[156:157], v[248:249], v[228:229]
	v_cvt_pk_bf16_f32 v228, v167, v169
	v_cvt_pk_bf16_f32 v229, v237, v239
	v_cvt_pk_bf16_f32 v230, v241, v243
	v_cvt_pk_bf16_f32 v231, v245, v247
	v_pk_mul_f32 v[62:63], v[62:63], v[166:167] op_sel_hi:[1,0]
	v_pk_mul_f32 v[60:61], v[60:61], v[166:167] op_sel_hi:[1,0]
	v_pk_mul_f32 v[58:59], v[58:59], v[166:167] op_sel_hi:[1,0]
	v_pk_mul_f32 v[56:57], v[56:57], v[166:167] op_sel_hi:[1,0]
	v_pk_mul_f32 v[54:55], v[54:55], v[166:167] op_sel_hi:[1,0]
	v_pk_mul_f32 v[52:53], v[52:53], v[166:167] op_sel_hi:[1,0]
	v_pk_mul_f32 v[50:51], v[50:51], v[166:167] op_sel_hi:[1,0]
	v_pk_mul_f32 v[48:49], v[48:49], v[166:167] op_sel_hi:[1,0]
	v_pk_fma_f32 v[154:155], v[154:155], v[182:183], v[96:97]
	v_cvt_pk_bf16_f32 v96, v173, v175
	v_cvt_pk_bf16_f32 v97, v177, v179
	v_cvt_pk_bf16_f32 v98, v181, v185
	v_cvt_pk_bf16_f32 v99, v187, v189
	v_pk_mul_f32 v[46:47], v[46:47], v[100:101] op_sel_hi:[1,0]
	v_pk_mul_f32 v[44:45], v[44:45], v[100:101] op_sel_hi:[1,0]
	v_pk_mul_f32 v[42:43], v[42:43], v[100:101] op_sel_hi:[1,0]
	v_pk_mul_f32 v[40:41], v[40:41], v[100:101] op_sel_hi:[1,0]
	v_pk_mul_f32 v[38:39], v[38:39], v[100:101] op_sel_hi:[1,0]
	v_pk_mul_f32 v[36:37], v[36:37], v[100:101] op_sel_hi:[1,0]
	v_pk_mul_f32 v[34:35], v[34:35], v[100:101] op_sel_hi:[1,0]
	v_pk_mul_f32 v[32:33], v[32:33], v[100:101] op_sel_hi:[1,0]
	v_mfma_f32_16x16x32_bf16 v[60:63], v[136:139], v[228:231], v[60:63]
	v_mfma_f32_16x16x32_bf16 v[56:59], v[140:143], v[228:231], v[56:59]
	v_mfma_f32_16x16x32_bf16 v[52:55], v[132:135], v[228:231], v[52:55]
	v_mfma_f32_16x16x32_bf16 v[48:51], v[128:131], v[228:231], v[48:51]
	v_mfma_f32_16x16x32_bf16 v[44:47], v[136:139], v[96:99], v[44:47]
	v_mfma_f32_16x16x32_bf16 v[40:43], v[140:143], v[96:99], v[40:43]
	v_mfma_f32_16x16x32_bf16 v[36:39], v[132:135], v[96:99], v[36:39]
	v_mfma_f32_16x16x32_bf16 v[32:35], v[128:131], v[96:99], v[32:35]
	s_waitcnt vmcnt(0)
	s_and_b64 vcc, exec, s[4:5]
	s_cbranch_vccnz .LBB0_203
	v_mov_b64_e32 v[108:109], v[112:113]
	v_mov_b64_e32 v[104:105], v[116:117]
	v_mov_b64_e32 v[100:101], v[120:121]
	v_mov_b64_e32 v[96:97], v[124:125]
	s_mov_b32 s82, s23
	s_mov_b32 s4, s24
	v_mov_b64_e32 v[110:111], v[114:115]
	v_mov_b64_e32 v[106:107], v[118:119]
	v_mov_b64_e32 v[102:103], v[122:123]
	v_mov_b64_e32 v[98:99], v[126:127]
	v_mov_b32_e32 v172, v201
	v_mov_b32_e32 v177, v205
	v_mov_b32_e32 v175, v206
	v_mov_b32_e32 v173, v202
	s_andn2_b64 vcc, exec, s[12:13]
	s_mov_b64 s[0:1], -1
	s_cbranch_vccz .LBB0_193
	s_branch .LBB0_198
